# ctx_combine (3 instances): all K-slice partial-sum loads and the x / gate loads of the four column groups issued together at the loop top instead of one load per full wait
# speedup vs baseline: 1.0057x; 1.0057x over previous
; DEVI void ctx_combine_phase(const Params& p, int l, int gi, float coef, int ln, int lwhich) {
;     ...
;   for (int rc = gw; rc < TC; rc += NW) {
;     f32x4* x4 = (f32x4*)(X + (size_t)(TL + rc) * D) + lane;
;     f32x4 v[4]; float ss = 0.f;
; #pragma unroll
;     for (int j = 0; j < 4; ++j) {
;       f32x4 sum = {0.f, 0.f, 0.f, 0.f};
; #pragma unroll
;       for (int sl = 0; sl < 7; ++sl) {
;         const uint2 w = *((const uint2*)(PS + ((size_t)sl * TC + rc) * D) + lane + 64 * j);
;         sum[0] += __uint_as_float(w.x << 16); sum[1] += __uint_as_float(w.x & 0xffff0000u); sum[2] += __uint_as_float(w.y << 16); sum[3] += __uint_as_float(w.y & 0xffff0000u);
;       }
;       const f32x4 xo = x4[64 * j], gv = gate4[64 * j];
; #pragma unroll
;       for (int q = 0; q < 4; ++q) v[j][q] = xo[q] + coef * gv[q] * sum[q];
;       x4[64 * j] = v[j];
;       ss += (v[j][0] * v[j][0] + v[j][1] * v[j][1]) + (v[j][2] * v[j][2] + v[j][3] * v[j][3]);
;     }
.LBB0_1040:
	v_add_co_u32_e32 v12, vcc, 0xfe800000, v50
	v_add_u32_e32 v16, 0x8000, v24
	s_nop 0
	v_addc_co_u32_e32 v13, vcc, -1, v51, vcc
	v_add_co_u32_e32 v14, vcc, 0xfec00000, v50
	v_ashrrev_i32_e32 v17, 31, v16
	s_nop 0
	v_addc_co_u32_e32 v15, vcc, -1, v51, vcc
	v_add_co_u32_e32 v22, vcc, 0xff000000, v50
	v_lshlrev_b64 v[0:1], 12, v[16:17]
	s_nop 0
	v_addc_co_u32_e32 v23, vcc, -1, v51, vcc
	v_add_co_u32_e32 v52, vcc, 0xff400000, v50
	v_lshl_add_u64 v[18:19], v[28:29], 0, v[0:1]
	s_nop 0
	v_addc_co_u32_e32 v53, vcc, -1, v51, vcc
	v_add_co_u32_e32 v54, vcc, 0xff800000, v50
	global_load_dwordx2 v[10:11], v[52:53], off offset:-1540
	s_nop 0
	v_addc_co_u32_e32 v55, vcc, -1, v51, vcc
	global_load_dwordx2 v[56:57], v[54:55], off offset:-1540
	global_load_dwordx2 v[0:1], v[12:13], off offset:-1540
	global_load_dwordx2 v[2:3], v[14:15], off offset:-1540
	global_load_dwordx2 v[6:7], v[22:23], off offset:-1540
	v_add_co_u32_e32 v98, vcc, 0xffc00000, v50
	s_nop 1
	v_addc_co_u32_e32 v99, vcc, -1, v51, vcc
	global_load_dwordx2 v[100:101], v[98:99], off offset:-1540
	global_load_dwordx2 v[102:103], v[50:51], off offset:-1540
	global_load_dwordx4 v[104:107], v[18:19], off
	global_load_dwordx4 v[108:111], v[26:27], off
	global_load_dwordx2 v[112:113], v[12:13], off offset:-1028
	global_load_dwordx2 v[114:115], v[14:15], off offset:-1028
	global_load_dwordx2 v[116:117], v[22:23], off offset:-1028
	global_load_dwordx2 v[118:119], v[52:53], off offset:-1028
	global_load_dwordx2 v[120:121], v[54:55], off offset:-1028
	global_load_dwordx2 v[122:123], v[98:99], off offset:-1028
	global_load_dwordx2 v[124:125], v[50:51], off offset:-1028
	global_load_dwordx4 v[126:129], v[18:19], off offset:1024
	global_load_dwordx4 v[130:133], v[26:27], off offset:1024
	global_load_dwordx2 v[134:135], v[12:13], off offset:-516
	global_load_dwordx2 v[136:137], v[14:15], off offset:-516
	global_load_dwordx2 v[138:139], v[22:23], off offset:-516
	global_load_dwordx2 v[140:141], v[52:53], off offset:-516
	global_load_dwordx2 v[142:143], v[54:55], off offset:-516
	global_load_dwordx2 v[144:145], v[98:99], off offset:-516
	global_load_dwordx2 v[146:147], v[50:51], off offset:-516
	global_load_dwordx4 v[152:155], v[18:19], off offset:2048
	global_load_dwordx4 v[156:159], v[26:27], off offset:2048
	global_load_dwordx2 v[160:161], v[12:13], off offset:-4
	global_load_dwordx2 v[162:163], v[14:15], off offset:-4
	global_load_dwordx2 v[164:165], v[22:23], off offset:-4
	global_load_dwordx2 v[166:167], v[52:53], off offset:-4
	global_load_dwordx2 v[168:169], v[54:55], off offset:-4
	global_load_dwordx2 v[170:171], v[98:99], off offset:-4
	global_load_dwordx2 v[172:173], v[50:51], off offset:-4
	global_load_dwordx4 v[176:179], v[18:19], off offset:3072
	global_load_dwordx4 v[180:183], v[26:27], off offset:3072
	v_lshlrev_b64 v[16:17], 11, v[16:17]
	v_add_u32_e32 v24, s2, v24
	s_waitcnt vmcnt(4)
	v_lshlrev_b32_e32 v60, 16, v10
	v_and_b32_e32 v61, 0xffff0000, v10
	v_lshlrev_b32_e32 v10, 16, v11
	s_waitcnt vmcnt(3)
	v_lshlrev_b32_e32 v70, 16, v56
	v_and_b32_e32 v71, 0xffff0000, v56
	v_add_co_u32_e32 v56, vcc, 0xffc00000, v50
	v_lshlrev_b32_e32 v58, 16, v57
	v_and_b32_e32 v59, 0xffff0000, v57
	v_addc_co_u32_e32 v57, vcc, -1, v51, vcc
	v_and_b32_e32 v11, 0xffff0000, v11
	s_waitcnt vmcnt(0)
	v_mov_b32_e32 v62, v100
	v_mov_b32_e32 v63, v101
	v_lshlrev_b32_e32 v72, 16, v62
	v_and_b32_e32 v73, 0xffff0000, v62
	v_lshlrev_b32_e32 v74, 16, v63
	v_and_b32_e32 v75, 0xffff0000, v63
	v_lshlrev_b32_e32 v4, 16, v0
	v_and_b32_e32 v5, 0xffff0000, v0
	v_lshlrev_b32_e32 v0, 16, v1
	v_and_b32_e32 v1, 0xffff0000, v1
	v_lshlrev_b32_e32 v8, 16, v2
	v_and_b32_e32 v9, 0xffff0000, v2
	v_lshlrev_b32_e32 v2, 16, v3
	v_and_b32_e32 v3, 0xffff0000, v3
	v_pk_add_f32 v[4:5], v[4:5], 0 op_sel_hi:[1,0]
	v_pk_add_f32 v[0:1], v[0:1], 0 op_sel_hi:[1,0]
	v_lshlrev_b32_e32 v20, 16, v6
	v_and_b32_e32 v21, 0xffff0000, v6
	v_lshlrev_b32_e32 v6, 16, v7
	v_and_b32_e32 v7, 0xffff0000, v7
	v_pk_add_f32 v[4:5], v[4:5], v[8:9]
	v_pk_add_f32 v[0:1], v[0:1], v[2:3]
	v_pk_add_f32 v[4:5], v[4:5], v[20:21]
	v_pk_add_f32 v[0:1], v[0:1], v[6:7]
	v_pk_add_f32 v[4:5], v[4:5], v[60:61]
	v_pk_add_f32 v[0:1], v[0:1], v[10:11]
	v_pk_add_f32 v[4:5], v[4:5], v[70:71]
	v_pk_add_f32 v[0:1], v[0:1], v[58:59]
	v_pk_add_f32 v[4:5], v[4:5], v[72:73]
	v_pk_add_f32 v[0:1], v[0:1], v[74:75]
	s_waitcnt vmcnt(0)
	v_mov_b32_e32 v62, v102
	v_mov_b32_e32 v63, v103
	v_lshlrev_b32_e32 v76, 16, v62
	v_and_b32_e32 v77, 0xffff0000, v62
	v_lshlrev_b32_e32 v78, 16, v63
	v_and_b32_e32 v79, 0xffff0000, v63
	v_pk_add_f32 v[4:5], v[4:5], v[76:77]
	v_pk_add_f32 v[0:1], v[0:1], v[78:79]
	s_waitcnt vmcnt(0)
	v_mov_b32_e32 v66, v108
	v_mov_b32_e32 v67, v109
	v_mov_b32_e32 v68, v110
	v_mov_b32_e32 v69, v111
	v_mov_b32_e32 v62, v104
	v_mov_b32_e32 v63, v105
	v_mov_b32_e32 v64, v106
	v_mov_b32_e32 v65, v107
	v_pk_mul_f32 v[8:9], v[66:67], 0.5 op_sel_hi:[1,0]
	v_pk_mul_f32 v[2:3], v[68:69], 0.5 op_sel_hi:[1,0]
	v_pk_fma_f32 v[8:9], v[4:5], v[8:9], v[62:63]
	v_pk_fma_f32 v[10:11], v[0:1], v[2:3], v[64:65]
	v_mov_b32_e32 v2, v9
	v_mov_b32_e32 v3, v11
	v_mov_b32_e32 v0, v8
	v_mov_b32_e32 v1, v10
	v_pk_mul_f32 v[2:3], v[2:3], v[2:3]
	global_store_dwordx4 v[18:19], v[8:11], off
	v_pk_fma_f32 v[0:1], v[0:1], v[0:1], v[2:3]
	s_nop 0
	v_pk_add_f32 v[20:21], v[0:1], v[0:1] op_sel:[0,1] op_sel_hi:[1,0]
	s_waitcnt vmcnt(0)
	v_mov_b32_e32 v0, v112
	v_mov_b32_e32 v1, v113
	v_lshlrev_b32_e32 v58, 16, v0
	v_and_b32_e32 v59, 0xffff0000, v0
	v_lshlrev_b32_e32 v4, 16, v1
	v_and_b32_e32 v5, 0xffff0000, v1
	v_pk_add_f32 v[58:59], v[58:59], 0 op_sel_hi:[1,0]
	v_pk_add_f32 v[4:5], v[4:5], 0 op_sel_hi:[1,0]
	s_waitcnt vmcnt(0)
; DEVI void ctx_combine_phase(const Params& p, int l, int gi, float coef, int ln, int lwhich) {
;     ...
;     for (int j = 0; j < 4; ++j) {
;       f32x4 sum = {0.f, 0.f, 0.f, 0.f};
; #pragma unroll
;       for (int sl = 0; sl < 7; ++sl) {
;         const uint2 w = *((const uint2*)(PS + ((size_t)sl * TC + rc) * D) + lane + 64 * j);
;         sum[0] += __uint_as_float(w.x << 16); sum[1] += __uint_as_float(w.x & 0xffff0000u); sum[2] += __uint_as_float(w.y << 16); sum[3] += __uint_as_float(w.y & 0xffff0000u);
;       }
;       const f32x4 xo = x4[64 * j], gv = gate4[64 * j];
; #pragma unroll
;       for (int q = 0; q < 4; ++q) v[j][q] = xo[q] + coef * gv[q] * sum[q];
;       x4[64 * j] = v[j];
;       ss += (v[j][0] * v[j][0] + v[j][1] * v[j][1]) + (v[j][2] * v[j][2] + v[j][3] * v[j][3]);
	v_mov_b32_e32 v0, v114
	v_mov_b32_e32 v1, v115
	v_lshlrev_b32_e32 v62, 16, v0
	v_and_b32_e32 v63, 0xffff0000, v0
	v_lshlrev_b32_e32 v6, 16, v1
	v_and_b32_e32 v7, 0xffff0000, v1
	v_pk_add_f32 v[58:59], v[58:59], v[62:63]
	v_pk_add_f32 v[4:5], v[4:5], v[6:7]
	s_waitcnt vmcnt(0)
	v_mov_b32_e32 v0, v116
	v_mov_b32_e32 v1, v117
	v_lshlrev_b32_e32 v66, 16, v0
	v_and_b32_e32 v67, 0xffff0000, v0
	v_lshlrev_b32_e32 v60, 16, v1
	v_and_b32_e32 v61, 0xffff0000, v1
	v_pk_add_f32 v[58:59], v[58:59], v[66:67]
	v_pk_add_f32 v[4:5], v[4:5], v[60:61]
	s_waitcnt vmcnt(0)
	v_mov_b32_e32 v0, v118
	v_mov_b32_e32 v1, v119
	v_lshlrev_b32_e32 v70, 16, v0
	v_and_b32_e32 v71, 0xffff0000, v0
	v_lshlrev_b32_e32 v64, 16, v1
	v_and_b32_e32 v65, 0xffff0000, v1
	v_pk_add_f32 v[58:59], v[58:59], v[70:71]
	v_pk_add_f32 v[4:5], v[4:5], v[64:65]
	s_waitcnt vmcnt(0)
	v_mov_b32_e32 v0, v120
	v_mov_b32_e32 v1, v121
	v_lshlrev_b32_e32 v74, 16, v0
	v_and_b32_e32 v75, 0xffff0000, v0
	v_lshlrev_b32_e32 v68, 16, v1
	v_and_b32_e32 v69, 0xffff0000, v1
	v_pk_add_f32 v[58:59], v[58:59], v[74:75]
	v_pk_add_f32 v[4:5], v[4:5], v[68:69]
	s_waitcnt vmcnt(0)
	v_mov_b32_e32 v0, v122
	v_mov_b32_e32 v1, v123
	v_lshlrev_b32_e32 v78, 16, v0
	v_and_b32_e32 v79, 0xffff0000, v0
	v_lshlrev_b32_e32 v72, 16, v1
	v_and_b32_e32 v73, 0xffff0000, v1
	v_pk_add_f32 v[58:59], v[58:59], v[78:79]
	v_pk_add_f32 v[4:5], v[4:5], v[72:73]
	s_waitcnt vmcnt(0)
	v_mov_b32_e32 v0, v124
	v_mov_b32_e32 v1, v125
	v_lshlrev_b32_e32 v80, 16, v0
	v_and_b32_e32 v81, 0xffff0000, v0
	v_lshlrev_b32_e32 v76, 16, v1
	v_and_b32_e32 v77, 0xffff0000, v1
	v_pk_add_f32 v[58:59], v[58:59], v[80:81]
	v_pk_add_f32 v[4:5], v[4:5], v[76:77]
	s_waitcnt vmcnt(0)
	v_mov_b32_e32 v82, v130
	v_mov_b32_e32 v83, v131
	v_mov_b32_e32 v84, v132
	v_mov_b32_e32 v85, v133
	v_mov_b32_e32 v0, v126
	v_mov_b32_e32 v1, v127
	v_mov_b32_e32 v2, v128
	v_mov_b32_e32 v3, v129
	v_pk_mul_f32 v[62:63], v[82:83], 0.5 op_sel_hi:[1,0]
	v_pk_mul_f32 v[6:7], v[84:85], 0.5 op_sel_hi:[1,0]
	v_pk_fma_f32 v[0:1], v[58:59], v[62:63], v[0:1]
	v_pk_fma_f32 v[2:3], v[4:5], v[6:7], v[2:3]
	v_mov_b32_e32 v6, v1
	v_mov_b32_e32 v7, v3
	v_mov_b32_e32 v4, v0
	v_mov_b32_e32 v5, v2
	v_pk_mul_f32 v[6:7], v[6:7], v[6:7]
	global_store_dwordx4 v[18:19], v[0:3], off offset:1024
	v_pk_fma_f32 v[4:5], v[4:5], v[4:5], v[6:7]
	s_nop 0
	v_pk_add_f32 v[58:59], v[4:5], v[4:5] op_sel:[0,1] op_sel_hi:[1,0]
	s_waitcnt vmcnt(0)
	v_mov_b32_e32 v4, v134
	v_mov_b32_e32 v5, v135
	v_lshlrev_b32_e32 v64, 16, v4
	v_and_b32_e32 v65, 0xffff0000, v4
	v_lshlrev_b32_e32 v60, 16, v5
	v_and_b32_e32 v61, 0xffff0000, v5
	v_pk_add_f32 v[64:65], v[64:65], 0 op_sel_hi:[1,0]
	v_pk_add_f32 v[60:61], v[60:61], 0 op_sel_hi:[1,0]
	s_waitcnt vmcnt(0)
	v_mov_b32_e32 v4, v136
	v_mov_b32_e32 v5, v137
	v_lshlrev_b32_e32 v68, 16, v4
	v_and_b32_e32 v69, 0xffff0000, v4
	v_lshlrev_b32_e32 v62, 16, v5
	v_and_b32_e32 v63, 0xffff0000, v5
	v_pk_add_f32 v[64:65], v[64:65], v[68:69]
	v_pk_add_f32 v[60:61], v[60:61], v[62:63]
	s_waitcnt vmcnt(0)
	v_mov_b32_e32 v4, v138
	v_mov_b32_e32 v5, v139
	v_lshlrev_b32_e32 v72, 16, v4
	v_and_b32_e32 v73, 0xffff0000, v4
	v_lshlrev_b32_e32 v66, 16, v5
	v_and_b32_e32 v67, 0xffff0000, v5
	v_pk_add_f32 v[64:65], v[64:65], v[72:73]
	v_pk_add_f32 v[60:61], v[60:61], v[66:67]
	s_waitcnt vmcnt(0)
	v_mov_b32_e32 v4, v140
	v_mov_b32_e32 v5, v141
	v_lshlrev_b32_e32 v76, 16, v4
	v_and_b32_e32 v77, 0xffff0000, v4
	v_lshlrev_b32_e32 v70, 16, v5
	v_and_b32_e32 v71, 0xffff0000, v5
	v_pk_add_f32 v[64:65], v[64:65], v[76:77]
	v_pk_add_f32 v[60:61], v[60:61], v[70:71]
	s_waitcnt vmcnt(0)
	v_mov_b32_e32 v4, v142
	v_mov_b32_e32 v5, v143
	v_lshlrev_b32_e32 v80, 16, v4
	v_and_b32_e32 v81, 0xffff0000, v4
	v_lshlrev_b32_e32 v74, 16, v5
	v_and_b32_e32 v75, 0xffff0000, v5
	v_pk_add_f32 v[64:65], v[64:65], v[80:81]
	v_pk_add_f32 v[60:61], v[60:61], v[74:75]
	s_waitcnt vmcnt(0)
	v_mov_b32_e32 v4, v144
	v_mov_b32_e32 v5, v145
	v_lshlrev_b32_e32 v84, 16, v4
	v_and_b32_e32 v85, 0xffff0000, v4
	v_lshlrev_b32_e32 v78, 16, v5
	v_and_b32_e32 v79, 0xffff0000, v5
	v_pk_add_f32 v[64:65], v[64:65], v[84:85]
	v_pk_add_f32 v[60:61], v[60:61], v[78:79]
	s_waitcnt vmcnt(0)
	v_mov_b32_e32 v4, v146
	v_mov_b32_e32 v5, v147
	v_lshlrev_b32_e32 v86, 16, v4
	v_and_b32_e32 v87, 0xffff0000, v4
	v_lshlrev_b32_e32 v82, 16, v5
	v_and_b32_e32 v83, 0xffff0000, v5
	v_pk_add_f32 v[64:65], v[64:65], v[86:87]
	v_pk_add_f32 v[60:61], v[60:61], v[82:83]
	s_waitcnt vmcnt(0)
	v_mov_b32_e32 v94, v156
	v_mov_b32_e32 v95, v157
	v_mov_b32_e32 v96, v158
	v_mov_b32_e32 v97, v159
	v_mov_b32_e32 v4, v152
	v_mov_b32_e32 v5, v153
	v_mov_b32_e32 v6, v154
	v_mov_b32_e32 v7, v155
	v_pk_mul_f32 v[68:69], v[94:95], 0.5 op_sel_hi:[1,0]
	v_pk_mul_f32 v[62:63], v[96:97], 0.5 op_sel_hi:[1,0]
	v_pk_fma_f32 v[4:5], v[64:65], v[68:69], v[4:5]
	v_pk_fma_f32 v[6:7], v[60:61], v[62:63], v[6:7]
	global_store_dwordx4 v[18:19], v[4:7], off offset:2048
	v_mul_f32_e32 v60, v5, v5
	v_mul_f32_e32 v62, v7, v7
	v_pk_fma_f32 v[60:61], v[4:5], v[4:5], v[60:61] op_sel_hi:[1,1,0]
	v_pk_fma_f32 v[62:63], v[6:7], v[6:7], v[62:63] op_sel_hi:[1,1,0]
	s_waitcnt vmcnt(0)
	v_mov_b32_e32 v12, v160
	v_mov_b32_e32 v13, v161
	v_lshlrev_b32_e32 v68, 16, v12
	v_and_b32_e32 v69, 0xffff0000, v12
	v_lshlrev_b32_e32 v64, 16, v13
	v_and_b32_e32 v65, 0xffff0000, v13
	v_pk_add_f32 v[68:69], v[68:69], 0 op_sel_hi:[1,0]
	v_pk_add_f32 v[64:65], v[64:65], 0 op_sel_hi:[1,0]
	s_waitcnt vmcnt(0)
	v_mov_b32_e32 v12, v162
	v_mov_b32_e32 v13, v163
	v_lshlrev_b32_e32 v70, 16, v12
	v_and_b32_e32 v71, 0xffff0000, v12
	v_lshlrev_b32_e32 v66, 16, v13
	v_and_b32_e32 v67, 0xffff0000, v13
	v_pk_add_f32 v[68:69], v[68:69], v[70:71]
	v_pk_add_f32 v[64:65], v[64:65], v[66:67]
	s_waitcnt vmcnt(0)
; DEVI unsigned pk_bf16(float lo, float hi) { unsigned r; asm volatile("v_cvt_pk_bf16_f32 %0, %1, %2" : "=v"(r) : "v"(lo), "v"(hi)); return r; }
; DEVI void ctx_combine_phase(const Params& p, int l, int gi, float coef, int ln, int lwhich) {
;     ...
;       for (int sl = 0; sl < 7; ++sl) {
;         const uint2 w = *((const uint2*)(PS + ((size_t)sl * TC + rc) * D) + lane + 64 * j);
;         sum[0] += __uint_as_float(w.x << 16); sum[1] += __uint_as_float(w.x & 0xffff0000u); sum[2] += __uint_as_float(w.y << 16); sum[3] += __uint_as_float(w.y & 0xffff0000u);
;       }
;       const f32x4 xo = x4[64 * j], gv = gate4[64 * j];
; #pragma unroll
;       for (int q = 0; q < 4; ++q) v[j][q] = xo[q] + coef * gv[q] * sum[q];
;       x4[64 * j] = v[j];
;       ss += (v[j][0] * v[j][0] + v[j][1] * v[j][1]) + (v[j][2] * v[j][2] + v[j][3] * v[j][3]);
;     }
;     if (ln >= 0) {
;       const f32x4* g4 = (const f32x4*)(p.in[6] + (size_t)(ln * 3 + lwhich) * D) + lane;
;       const f32x4* sh4 = (const f32x4*)(MOD + (size_t)((ln * 9 + 8) * 9 + lwhich * 3) * D) + lane;
;       const f32x4* sc4 = sh4 + D / 4;
;       const float rinv = rsqrtf(wave_sum(ss, lane) * (1.f / D) + 1e-6f);
;       uint2* o8 = (uint2*)(H + (size_t)(TL + rc) * D) + lane;
; #pragma unroll
;       for (int j = 0; j < 4; ++j) {
;         const f32x4 g = g4[64 * j], sh = sh4[64 * j], sc = sc4[64 * j];
;         f32x4 y;
; #pragma unroll
;         for (int q = 0; q < 4; ++q) y[q] = v[j][q] * rinv * g[q] * (1.f + sc[q]) + sh[q];
;         uint2 o; o.x = pk_bf16(y[0], y[1]); o.y = pk_bf16(y[2], y[3]); o8[64 * j] = o;
;       }
	v_mov_b32_e32 v12, v164
	v_mov_b32_e32 v13, v165
	v_lshlrev_b32_e32 v72, 16, v12
	v_and_b32_e32 v73, 0xffff0000, v12
	v_lshlrev_b32_e32 v22, 16, v13
	v_and_b32_e32 v23, 0xffff0000, v13
	v_pk_add_f32 v[68:69], v[68:69], v[72:73]
	v_pk_add_f32 v[22:23], v[64:65], v[22:23]
	s_waitcnt vmcnt(0)
	v_mov_b32_e32 v12, v166
	v_mov_b32_e32 v13, v167
	v_lshlrev_b32_e32 v74, 16, v12
	v_and_b32_e32 v75, 0xffff0000, v12
	v_lshlrev_b32_e32 v52, 16, v13
	v_and_b32_e32 v53, 0xffff0000, v13
	v_pk_add_f32 v[68:69], v[68:69], v[74:75]
	v_pk_add_f32 v[22:23], v[22:23], v[52:53]
	s_waitcnt vmcnt(0)
	v_mov_b32_e32 v12, v168
	v_mov_b32_e32 v13, v169
	v_lshlrev_b32_e32 v76, 16, v12
	v_and_b32_e32 v77, 0xffff0000, v12
	v_lshlrev_b32_e32 v54, 16, v13
	v_and_b32_e32 v55, 0xffff0000, v13
	v_pk_add_f32 v[68:69], v[68:69], v[76:77]
	v_pk_add_f32 v[22:23], v[22:23], v[54:55]
	s_waitcnt vmcnt(0)
	v_mov_b32_e32 v12, v170
	v_mov_b32_e32 v13, v171
	v_lshlrev_b32_e32 v80, 16, v12
	v_and_b32_e32 v81, 0xffff0000, v12
	v_lshlrev_b32_e32 v56, 16, v13
	v_and_b32_e32 v57, 0xffff0000, v13
	v_pk_add_f32 v[68:69], v[68:69], v[80:81]
	v_pk_add_f32 v[22:23], v[22:23], v[56:57]
	v_lshl_add_u64 v[50:51], v[50:51], 0, s[26:27]
	s_waitcnt vmcnt(0)
	v_mov_b32_e32 v12, v172
	v_mov_b32_e32 v13, v173
	v_lshlrev_b32_e32 v82, 16, v12
	v_and_b32_e32 v83, 0xffff0000, v12
	v_lshlrev_b32_e32 v78, 16, v13
	v_and_b32_e32 v79, 0xffff0000, v13
	v_pk_add_f32 v[68:69], v[68:69], v[82:83]
	v_pk_add_f32 v[22:23], v[22:23], v[78:79]
	s_waitcnt vmcnt(0)
	v_mov_b32_e32 v84, v180
	v_mov_b32_e32 v85, v181
	v_mov_b32_e32 v86, v182
	v_mov_b32_e32 v87, v183
	v_mov_b32_e32 v12, v176
	v_mov_b32_e32 v13, v177
	v_mov_b32_e32 v14, v178
	v_mov_b32_e32 v15, v179
	v_pk_mul_f32 v[70:71], v[84:85], 0.5 op_sel_hi:[1,0]
	v_pk_mul_f32 v[52:53], v[86:87], 0.5 op_sel_hi:[1,0]
	v_pk_fma_f32 v[12:13], v[68:69], v[70:71], v[12:13]
	v_pk_fma_f32 v[14:15], v[22:23], v[52:53], v[14:15]
	global_store_dwordx4 v[18:19], v[12:15], off offset:3072
	v_pk_mul_f32 v[18:19], v[12:13], v[12:13]
	v_pk_mul_f32 v[22:23], v[14:15], v[14:15]
	v_mov_b32_e32 v21, v18
	v_mov_b32_e32 v59, v19
	v_mov_b32_e32 v61, v22
	v_mov_b32_e32 v63, v23
	v_pk_add_f32 v[18:19], v[20:21], v[58:59]
	v_pk_add_f32 v[20:21], v[60:61], v[62:63]
	v_lshl_add_u64 v[52:53], v[30:31], 0, v[16:17]
	v_pk_add_f32 v[18:19], v[18:19], v[20:21]
	s_nop 0
	v_add_f32_e32 v18, v18, v19
	ds_bpermute_b32 v19, v88, v18
	s_waitcnt lgkmcnt(0)
	v_add_f32_e32 v18, v18, v19
	ds_bpermute_b32 v19, v89, v18
	s_waitcnt lgkmcnt(0)
	v_add_f32_e32 v18, v18, v19
	ds_bpermute_b32 v19, v90, v18
	s_waitcnt lgkmcnt(0)
	v_add_f32_e32 v18, v18, v19
	ds_bpermute_b32 v19, v91, v18
	s_waitcnt lgkmcnt(0)
	v_add_f32_e32 v18, v18, v19
	ds_bpermute_b32 v19, v92, v18
	s_waitcnt lgkmcnt(0)
	v_add_f32_e32 v18, v18, v19
	ds_bpermute_b32 v19, v93, v18
	s_waitcnt lgkmcnt(0)
	v_add_f32_e32 v18, v18, v19
	v_fmamk_f32 v18, v18, 0x3a800000, v230
	v_cmp_gt_f32_e32 vcc, s24, v18
	v_mul_f32_e32 v19, 0x4b800000, v18
	s_nop 0
	v_cndmask_b32_e32 v18, v18, v19, vcc
	v_rsq_f32_e32 v18, v18
	s_nop 0
	v_mul_f32_e32 v19, 0x45800000, v18
	v_cndmask_b32_e32 v25, v18, v19, vcc
	global_load_dwordx4 v[20:23], v[48:49], off
	global_load_dwordx4 v[16:19], v[32:33], off
	global_load_dwordx4 v[54:57], v[34:35], off
	v_mul_f32_e32 v8, v8, v25
	v_mul_f32_e32 v9, v9, v25
	v_mul_f32_e32 v10, v10, v25
	v_mul_f32_e32 v11, v11, v25
	v_mul_f32_e32 v0, v0, v25
	v_mul_f32_e32 v1, v1, v25
	v_mul_f32_e32 v2, v2, v25
	v_mul_f32_e32 v3, v3, v25
	v_mul_f32_e32 v4, v4, v25
	v_mul_f32_e32 v12, v12, v25
	v_cmp_lt_i32_e32 vcc, s25, v24
	s_or_b64 s[6:7], vcc, s[6:7]
	s_waitcnt vmcnt(2)
	v_mul_f32_e32 v8, v20, v8
	v_mul_f32_e32 v9, v21, v9
	s_waitcnt vmcnt(0)
	v_add_f32_e32 v20, 1.0, v54
	v_fma_f32 v8, v20, v8, v16
	v_add_f32_e32 v16, 1.0, v55
	v_fma_f32 v9, v16, v9, v17
	v_mul_f32_e32 v10, v22, v10
	v_add_f32_e32 v16, 1.0, v56
	v_fma_f32 v10, v16, v10, v18
	v_mul_f32_e32 v11, v23, v11
	v_add_f32_e32 v16, 1.0, v57
	v_fmac_f32_e32 v19, v16, v11
	v_cvt_pk_bf16_f32 v8, v8, v9
	v_cvt_pk_bf16_f32 v9, v10, v19
	global_store_dwordx2 v[52:53], v[8:9], off
	global_load_dwordx4 v[8:11], v[48:49], off offset:1024
	s_nop 0
	global_load_dwordx4 v[16:19], v[36:37], off
	global_load_dwordx4 v[20:23], v[38:39], off
	s_waitcnt vmcnt(2)
	v_mul_f32_e32 v0, v8, v0
	v_mul_f32_e32 v1, v9, v1
	s_waitcnt vmcnt(0)
	v_add_f32_e32 v8, 1.0, v20
	v_fma_f32 v0, v8, v0, v16
	v_add_f32_e32 v8, 1.0, v21
	v_fma_f32 v1, v8, v1, v17
	v_mul_f32_e32 v2, v10, v2
	v_add_f32_e32 v8, 1.0, v22
	v_fma_f32 v2, v8, v2, v18
	v_mul_f32_e32 v3, v11, v3
	v_add_f32_e32 v8, 1.0, v23
	v_fmac_f32_e32 v19, v8, v3
	v_cvt_pk_bf16_f32 v0, v0, v1
	v_cvt_pk_bf16_f32 v1, v2, v19
	global_store_dwordx2 v[52:53], v[0:1], off offset:512
	global_load_dwordx4 v[0:3], v[48:49], off offset:2048
	s_nop 0
	global_load_dwordx4 v[8:11], v[40:41], off
	global_load_dwordx4 v[16:19], v[42:43], off
	s_waitcnt vmcnt(2)
	v_mul_f32_e32 v0, v4, v0
	s_waitcnt vmcnt(0)
	v_add_f32_e32 v4, 1.0, v16
	v_fma_f32 v0, v0, v4, v8
	v_mul_f32_e32 v4, v5, v25
	v_mul_f32_e32 v1, v4, v1
	v_add_f32_e32 v4, 1.0, v17
	v_fma_f32 v1, v1, v4, v9
	v_mul_f32_e32 v4, v6, v25
	v_mul_f32_e32 v2, v4, v2
	v_add_f32_e32 v4, 1.0, v18
	v_fma_f32 v2, v2, v4, v10
	v_mul_f32_e32 v4, v7, v25
	v_mul_f32_e32 v3, v4, v3
	v_add_f32_e32 v4, 1.0, v19
	v_fmac_f32_e32 v11, v3, v4
	v_cvt_pk_bf16_f32 v0, v0, v1
	v_cvt_pk_bf16_f32 v1, v2, v11
	global_store_dwordx2 v[52:53], v[0:1], off offset:1024
	global_load_dwordx4 v[0:3], v[48:49], off offset:3072
	s_nop 0
	global_load_dwordx4 v[4:7], v[44:45], off
	global_load_dwordx4 v[8:11], v[46:47], off
	s_waitcnt vmcnt(2)
	v_mul_f32_e32 v0, v12, v0
	s_waitcnt vmcnt(0)
	v_add_f32_e32 v8, 1.0, v8
	v_fma_f32 v0, v0, v8, v4
	v_mul_f32_e32 v4, v13, v25
	v_mul_f32_e32 v1, v4, v1
	v_add_f32_e32 v4, 1.0, v9
	v_fma_f32 v1, v1, v4, v5
	v_mul_f32_e32 v4, v14, v25
	v_mul_f32_e32 v2, v4, v2
	v_add_f32_e32 v4, 1.0, v10
	v_fma_f32 v2, v2, v4, v6
	v_mul_f32_e32 v4, v15, v25
	v_mul_f32_e32 v3, v4, v3
	v_add_f32_e32 v4, 1.0, v11
	v_fmac_f32_e32 v7, v3, v4
	v_cvt_pk_bf16_f32 v0, v0, v1
	v_cvt_pk_bf16_f32 v1, v2, v7
	global_store_dwordx2 v[52:53], v[0:1], off offset:1536
	s_andn2_b64 exec, exec, s[6:7]
	s_cbranch_execnz .LBB0_1040

; DEVI void ctx_combine_phase(const Params& p, int l, int gi, float coef, int ln, int lwhich) {
;     ...
;   for (int rc = gw; rc < TC; rc += NW) {
;     f32x4* x4 = (f32x4*)(X + (size_t)(TL + rc) * D) + lane;
;     f32x4 v[4]; float ss = 0.f;
; #pragma unroll
;     for (int j = 0; j < 4; ++j) {
;       f32x4 sum = {0.f, 0.f, 0.f, 0.f};
; #pragma unroll
;       for (int sl = 0; sl < 7; ++sl) {
;         const uint2 w = *((const uint2*)(PS + ((size_t)sl * TC + rc) * D) + lane + 64 * j);
;         sum[0] += __uint_as_float(w.x << 16); sum[1] += __uint_as_float(w.x & 0xffff0000u); sum[2] += __uint_as_float(w.y << 16); sum[3] += __uint_as_float(w.y & 0xffff0000u);
;       }
;       const f32x4 xo = x4[64 * j], gv = gate4[64 * j];
; #pragma unroll
;       for (int q = 0; q < 4; ++q) v[j][q] = xo[q] + coef * gv[q] * sum[q];
;       x4[64 * j] = v[j];
;       ss += (v[j][0] * v[j][0] + v[j][1] * v[j][1]) + (v[j][2] * v[j][2] + v[j][3] * v[j][3]);
.LBB0_1929:
	v_add_co_u32_e32 v12, vcc, 0xfe800000, v50
	v_add_u32_e32 v16, 0x8000, v24
	s_nop 0
	v_addc_co_u32_e32 v13, vcc, -1, v51, vcc
	v_add_co_u32_e32 v14, vcc, 0xfec00000, v50
	v_ashrrev_i32_e32 v17, 31, v16
	s_nop 0
	v_addc_co_u32_e32 v15, vcc, -1, v51, vcc
	v_add_co_u32_e32 v22, vcc, 0xff000000, v50
	v_lshlrev_b64 v[0:1], 12, v[16:17]
	s_nop 0
	v_addc_co_u32_e32 v23, vcc, -1, v51, vcc
	v_add_co_u32_e32 v52, vcc, 0xff400000, v50
	v_lshl_add_u64 v[18:19], v[28:29], 0, v[0:1]
	s_nop 0
	v_addc_co_u32_e32 v53, vcc, -1, v51, vcc
	v_add_co_u32_e32 v54, vcc, 0xff800000, v50
	global_load_dwordx2 v[20:21], v[52:53], off offset:-1540
	s_nop 0
	v_addc_co_u32_e32 v55, vcc, -1, v51, vcc
	global_load_dwordx2 v[56:57], v[54:55], off offset:-1540
	global_load_dwordx2 v[0:1], v[12:13], off offset:-1540
	global_load_dwordx2 v[4:5], v[14:15], off offset:-1540
	global_load_dwordx2 v[10:11], v[22:23], off offset:-1540
	v_add_co_u32_e32 v98, vcc, 0xffc00000, v50
	s_nop 1
	v_addc_co_u32_e32 v99, vcc, -1, v51, vcc
	global_load_dwordx2 v[100:101], v[98:99], off offset:-1540
	global_load_dwordx2 v[102:103], v[50:51], off offset:-1540
	global_load_dwordx4 v[104:107], v[18:19], off
	global_load_dwordx4 v[108:111], v[26:27], off
	global_load_dwordx2 v[112:113], v[12:13], off offset:-1028
	global_load_dwordx2 v[114:115], v[14:15], off offset:-1028
	global_load_dwordx2 v[116:117], v[22:23], off offset:-1028
	global_load_dwordx2 v[118:119], v[52:53], off offset:-1028
	global_load_dwordx2 v[120:121], v[54:55], off offset:-1028
	global_load_dwordx2 v[122:123], v[98:99], off offset:-1028
	global_load_dwordx2 v[124:125], v[50:51], off offset:-1028
	global_load_dwordx4 v[126:129], v[18:19], off offset:1024
	global_load_dwordx4 v[130:133], v[26:27], off offset:1024
	global_load_dwordx2 v[134:135], v[12:13], off offset:-516
	global_load_dwordx2 v[136:137], v[14:15], off offset:-516
	global_load_dwordx2 v[138:139], v[22:23], off offset:-516
	global_load_dwordx2 v[140:141], v[52:53], off offset:-516
	global_load_dwordx2 v[142:143], v[54:55], off offset:-516
	global_load_dwordx2 v[144:145], v[98:99], off offset:-516
	global_load_dwordx2 v[146:147], v[50:51], off offset:-516
	global_load_dwordx4 v[152:155], v[18:19], off offset:2048
	global_load_dwordx4 v[156:159], v[26:27], off offset:2048
	global_load_dwordx2 v[160:161], v[12:13], off offset:-4
	global_load_dwordx2 v[162:163], v[14:15], off offset:-4
	global_load_dwordx2 v[164:165], v[22:23], off offset:-4
	global_load_dwordx2 v[166:167], v[52:53], off offset:-4
	global_load_dwordx2 v[168:169], v[54:55], off offset:-4
	global_load_dwordx2 v[170:171], v[98:99], off offset:-4
	global_load_dwordx2 v[172:173], v[50:51], off offset:-4
	global_load_dwordx4 v[176:179], v[18:19], off offset:3072
	global_load_dwordx4 v[180:183], v[26:27], off offset:3072
	v_lshlrev_b64 v[16:17], 11, v[16:17]
	v_add_u32_e32 v24, s2, v24
	s_waitcnt vmcnt(4)
	v_lshlrev_b32_e32 v58, 16, v20
	v_and_b32_e32 v59, 0xffff0000, v20
	v_lshlrev_b32_e32 v20, 16, v21
	s_waitcnt vmcnt(3)
	v_lshlrev_b32_e32 v68, 16, v56
	v_and_b32_e32 v69, 0xffff0000, v56
	v_add_co_u32_e32 v56, vcc, 0xffc00000, v50
	v_lshlrev_b32_e32 v70, 16, v57
	v_and_b32_e32 v71, 0xffff0000, v57
	v_addc_co_u32_e32 v57, vcc, -1, v51, vcc
	v_and_b32_e32 v21, 0xffff0000, v21
	s_waitcnt vmcnt(0)
	v_mov_b32_e32 v60, v100
	v_mov_b32_e32 v61, v101
	v_lshlrev_b32_e32 v72, 16, v60
	v_and_b32_e32 v73, 0xffff0000, v60
	v_lshlrev_b32_e32 v74, 16, v61
	v_and_b32_e32 v75, 0xffff0000, v61
	v_lshlrev_b32_e32 v2, 16, v0
	v_and_b32_e32 v3, 0xffff0000, v0
	v_lshlrev_b32_e32 v0, 16, v1
	v_and_b32_e32 v1, 0xffff0000, v1
	v_lshlrev_b32_e32 v6, 16, v4
	v_and_b32_e32 v7, 0xffff0000, v4
	v_lshlrev_b32_e32 v4, 16, v5
	v_and_b32_e32 v5, 0xffff0000, v5
	v_pk_add_f32 v[2:3], v[2:3], 0 op_sel_hi:[1,0]
	v_pk_add_f32 v[0:1], v[0:1], 0 op_sel_hi:[1,0]
	v_lshlrev_b32_e32 v8, 16, v10
	v_and_b32_e32 v9, 0xffff0000, v10
	v_lshlrev_b32_e32 v10, 16, v11
	v_and_b32_e32 v11, 0xffff0000, v11
	v_pk_add_f32 v[2:3], v[2:3], v[6:7]
	v_pk_add_f32 v[0:1], v[0:1], v[4:5]
	v_pk_add_f32 v[2:3], v[2:3], v[8:9]
	v_pk_add_f32 v[0:1], v[0:1], v[10:11]
	v_pk_add_f32 v[2:3], v[2:3], v[58:59]
	v_pk_add_f32 v[0:1], v[0:1], v[20:21]
	v_pk_add_f32 v[2:3], v[2:3], v[68:69]
	v_pk_add_f32 v[0:1], v[0:1], v[70:71]
	v_pk_add_f32 v[2:3], v[2:3], v[72:73]
	v_pk_add_f32 v[0:1], v[0:1], v[74:75]
	s_waitcnt vmcnt(0)
	v_mov_b32_e32 v60, v102
	v_mov_b32_e32 v61, v103
	v_lshlrev_b32_e32 v76, 16, v60
	v_and_b32_e32 v77, 0xffff0000, v60
	v_lshlrev_b32_e32 v78, 16, v61
	v_and_b32_e32 v79, 0xffff0000, v61
	v_pk_add_f32 v[2:3], v[2:3], v[76:77]
	v_pk_add_f32 v[0:1], v[0:1], v[78:79]
	s_waitcnt vmcnt(0)
	v_mov_b32_e32 v64, v108
	v_mov_b32_e32 v65, v109
	v_mov_b32_e32 v66, v110
	v_mov_b32_e32 v67, v111
	v_mov_b32_e32 v60, v104
	v_mov_b32_e32 v61, v105
	v_mov_b32_e32 v62, v106
	v_mov_b32_e32 v63, v107
	v_pk_fma_f32 v[8:9], v[2:3], v[64:65], v[60:61]
	v_pk_fma_f32 v[10:11], v[0:1], v[66:67], v[62:63]
	v_mov_b32_e32 v2, v9
	v_mov_b32_e32 v3, v11
	v_mov_b32_e32 v0, v8
	v_mov_b32_e32 v1, v10
	v_pk_mul_f32 v[2:3], v[2:3], v[2:3]
	global_store_dwordx4 v[18:19], v[8:11], off
	v_pk_fma_f32 v[0:1], v[0:1], v[0:1], v[2:3]
	s_nop 0
	v_pk_add_f32 v[20:21], v[0:1], v[0:1] op_sel:[0,1] op_sel_hi:[1,0]
	s_waitcnt vmcnt(0)
	v_mov_b32_e32 v0, v112
	v_mov_b32_e32 v1, v113
	v_lshlrev_b32_e32 v58, 16, v0
	v_and_b32_e32 v59, 0xffff0000, v0
	v_lshlrev_b32_e32 v4, 16, v1
	v_and_b32_e32 v5, 0xffff0000, v1
	v_pk_add_f32 v[58:59], v[58:59], 0 op_sel_hi:[1,0]
	v_pk_add_f32 v[4:5], v[4:5], 0 op_sel_hi:[1,0]
	s_waitcnt vmcnt(0)
; DEVI void ctx_combine_phase(const Params& p, int l, int gi, float coef, int ln, int lwhich) {
;     ...
;     for (int j = 0; j < 4; ++j) {
;       f32x4 sum = {0.f, 0.f, 0.f, 0.f};
; #pragma unroll
;       for (int sl = 0; sl < 7; ++sl) {
;         const uint2 w = *((const uint2*)(PS + ((size_t)sl * TC + rc) * D) + lane + 64 * j);
;         sum[0] += __uint_as_float(w.x << 16); sum[1] += __uint_as_float(w.x & 0xffff0000u); sum[2] += __uint_as_float(w.y << 16); sum[3] += __uint_as_float(w.y & 0xffff0000u);
;       }
;       const f32x4 xo = x4[64 * j], gv = gate4[64 * j];
; #pragma unroll
;       for (int q = 0; q < 4; ++q) v[j][q] = xo[q] + coef * gv[q] * sum[q];
;       x4[64 * j] = v[j];
;       ss += (v[j][0] * v[j][0] + v[j][1] * v[j][1]) + (v[j][2] * v[j][2] + v[j][3] * v[j][3]);
	v_mov_b32_e32 v0, v114
	v_mov_b32_e32 v1, v115
	v_lshlrev_b32_e32 v62, 16, v0
	v_and_b32_e32 v63, 0xffff0000, v0
	v_lshlrev_b32_e32 v6, 16, v1
	v_and_b32_e32 v7, 0xffff0000, v1
	v_pk_add_f32 v[58:59], v[58:59], v[62:63]
	v_pk_add_f32 v[4:5], v[4:5], v[6:7]
	s_waitcnt vmcnt(0)
	v_mov_b32_e32 v0, v116
	v_mov_b32_e32 v1, v117
	v_lshlrev_b32_e32 v66, 16, v0
	v_and_b32_e32 v67, 0xffff0000, v0
	v_lshlrev_b32_e32 v60, 16, v1
	v_and_b32_e32 v61, 0xffff0000, v1
	v_pk_add_f32 v[58:59], v[58:59], v[66:67]
	v_pk_add_f32 v[4:5], v[4:5], v[60:61]
	s_waitcnt vmcnt(0)
	v_mov_b32_e32 v0, v118
	v_mov_b32_e32 v1, v119
	v_lshlrev_b32_e32 v70, 16, v0
	v_and_b32_e32 v71, 0xffff0000, v0
	v_lshlrev_b32_e32 v64, 16, v1
	v_and_b32_e32 v65, 0xffff0000, v1
	v_pk_add_f32 v[58:59], v[58:59], v[70:71]
	v_pk_add_f32 v[4:5], v[4:5], v[64:65]
	s_waitcnt vmcnt(0)
	v_mov_b32_e32 v0, v120
	v_mov_b32_e32 v1, v121
	v_lshlrev_b32_e32 v74, 16, v0
	v_and_b32_e32 v75, 0xffff0000, v0
	v_lshlrev_b32_e32 v68, 16, v1
	v_and_b32_e32 v69, 0xffff0000, v1
	v_pk_add_f32 v[58:59], v[58:59], v[74:75]
	v_pk_add_f32 v[4:5], v[4:5], v[68:69]
	s_waitcnt vmcnt(0)
	v_mov_b32_e32 v0, v122
	v_mov_b32_e32 v1, v123
	v_lshlrev_b32_e32 v78, 16, v0
	v_and_b32_e32 v79, 0xffff0000, v0
	v_lshlrev_b32_e32 v72, 16, v1
	v_and_b32_e32 v73, 0xffff0000, v1
	v_pk_add_f32 v[58:59], v[58:59], v[78:79]
	v_pk_add_f32 v[4:5], v[4:5], v[72:73]
	s_waitcnt vmcnt(0)
	v_mov_b32_e32 v0, v124
	v_mov_b32_e32 v1, v125
	v_lshlrev_b32_e32 v80, 16, v0
	v_and_b32_e32 v81, 0xffff0000, v0
	v_lshlrev_b32_e32 v76, 16, v1
	v_and_b32_e32 v77, 0xffff0000, v1
	v_pk_add_f32 v[58:59], v[58:59], v[80:81]
	v_pk_add_f32 v[4:5], v[4:5], v[76:77]
	s_waitcnt vmcnt(0)
	v_mov_b32_e32 v82, v130
	v_mov_b32_e32 v83, v131
	v_mov_b32_e32 v84, v132
	v_mov_b32_e32 v85, v133
	v_mov_b32_e32 v0, v126
	v_mov_b32_e32 v1, v127
	v_mov_b32_e32 v2, v128
	v_mov_b32_e32 v3, v129
	v_pk_fma_f32 v[0:1], v[58:59], v[82:83], v[0:1]
	v_pk_fma_f32 v[2:3], v[4:5], v[84:85], v[2:3]
	v_mov_b32_e32 v6, v1
	v_mov_b32_e32 v7, v3
	v_mov_b32_e32 v4, v0
	v_mov_b32_e32 v5, v2
	v_pk_mul_f32 v[6:7], v[6:7], v[6:7]
	global_store_dwordx4 v[18:19], v[0:3], off offset:1024
	v_pk_fma_f32 v[4:5], v[4:5], v[4:5], v[6:7]
	s_nop 0
	v_pk_add_f32 v[58:59], v[4:5], v[4:5] op_sel:[0,1] op_sel_hi:[1,0]
	s_waitcnt vmcnt(0)
	v_mov_b32_e32 v4, v134
	v_mov_b32_e32 v5, v135
	v_lshlrev_b32_e32 v64, 16, v4
	v_and_b32_e32 v65, 0xffff0000, v4
	v_lshlrev_b32_e32 v60, 16, v5
	v_and_b32_e32 v61, 0xffff0000, v5
	v_pk_add_f32 v[64:65], v[64:65], 0 op_sel_hi:[1,0]
	v_pk_add_f32 v[60:61], v[60:61], 0 op_sel_hi:[1,0]
	s_waitcnt vmcnt(0)
	v_mov_b32_e32 v4, v136
	v_mov_b32_e32 v5, v137
	v_lshlrev_b32_e32 v68, 16, v4
	v_and_b32_e32 v69, 0xffff0000, v4
	v_lshlrev_b32_e32 v62, 16, v5
	v_and_b32_e32 v63, 0xffff0000, v5
	v_pk_add_f32 v[64:65], v[64:65], v[68:69]
	v_pk_add_f32 v[60:61], v[60:61], v[62:63]
	s_waitcnt vmcnt(0)
	v_mov_b32_e32 v4, v138
	v_mov_b32_e32 v5, v139
	v_lshlrev_b32_e32 v72, 16, v4
	v_and_b32_e32 v73, 0xffff0000, v4
	v_lshlrev_b32_e32 v66, 16, v5
	v_and_b32_e32 v67, 0xffff0000, v5
	v_pk_add_f32 v[64:65], v[64:65], v[72:73]
	v_pk_add_f32 v[60:61], v[60:61], v[66:67]
	s_waitcnt vmcnt(0)
	v_mov_b32_e32 v4, v140
	v_mov_b32_e32 v5, v141
	v_lshlrev_b32_e32 v76, 16, v4
	v_and_b32_e32 v77, 0xffff0000, v4
	v_lshlrev_b32_e32 v70, 16, v5
	v_and_b32_e32 v71, 0xffff0000, v5
	v_pk_add_f32 v[64:65], v[64:65], v[76:77]
	v_pk_add_f32 v[60:61], v[60:61], v[70:71]
	s_waitcnt vmcnt(0)
	v_mov_b32_e32 v4, v142
	v_mov_b32_e32 v5, v143
	v_lshlrev_b32_e32 v80, 16, v4
	v_and_b32_e32 v81, 0xffff0000, v4
	v_lshlrev_b32_e32 v74, 16, v5
	v_and_b32_e32 v75, 0xffff0000, v5
	v_pk_add_f32 v[64:65], v[64:65], v[80:81]
	v_pk_add_f32 v[60:61], v[60:61], v[74:75]
	s_waitcnt vmcnt(0)
	v_mov_b32_e32 v4, v144
	v_mov_b32_e32 v5, v145
	v_lshlrev_b32_e32 v84, 16, v4
	v_and_b32_e32 v85, 0xffff0000, v4
	v_lshlrev_b32_e32 v78, 16, v5
	v_and_b32_e32 v79, 0xffff0000, v5
	v_pk_add_f32 v[64:65], v[64:65], v[84:85]
	v_pk_add_f32 v[60:61], v[60:61], v[78:79]
	s_waitcnt vmcnt(0)
	v_mov_b32_e32 v4, v146
	v_mov_b32_e32 v5, v147
	v_lshlrev_b32_e32 v86, 16, v4
	v_and_b32_e32 v87, 0xffff0000, v4
	v_lshlrev_b32_e32 v82, 16, v5
	v_and_b32_e32 v83, 0xffff0000, v5
	v_pk_add_f32 v[64:65], v[64:65], v[86:87]
	v_pk_add_f32 v[60:61], v[60:61], v[82:83]
	s_waitcnt vmcnt(0)
	v_mov_b32_e32 v94, v156
	v_mov_b32_e32 v95, v157
	v_mov_b32_e32 v96, v158
	v_mov_b32_e32 v97, v159
	v_mov_b32_e32 v4, v152
	v_mov_b32_e32 v5, v153
	v_mov_b32_e32 v6, v154
	v_mov_b32_e32 v7, v155
	v_pk_fma_f32 v[4:5], v[64:65], v[94:95], v[4:5]
	v_pk_fma_f32 v[6:7], v[60:61], v[96:97], v[6:7]
	global_store_dwordx4 v[18:19], v[4:7], off offset:2048
	v_mul_f32_e32 v60, v5, v5
	v_mul_f32_e32 v62, v7, v7
	v_pk_fma_f32 v[60:61], v[4:5], v[4:5], v[60:61] op_sel_hi:[1,1,0]
	v_pk_fma_f32 v[62:63], v[6:7], v[6:7], v[62:63] op_sel_hi:[1,1,0]
	s_waitcnt vmcnt(0)
	v_mov_b32_e32 v12, v160
	v_mov_b32_e32 v13, v161
	v_lshlrev_b32_e32 v68, 16, v12
	v_and_b32_e32 v69, 0xffff0000, v12
	v_lshlrev_b32_e32 v64, 16, v13
	v_and_b32_e32 v65, 0xffff0000, v13
	v_pk_add_f32 v[68:69], v[68:69], 0 op_sel_hi:[1,0]
	v_pk_add_f32 v[64:65], v[64:65], 0 op_sel_hi:[1,0]
	s_waitcnt vmcnt(0)
	v_mov_b32_e32 v12, v162
	v_mov_b32_e32 v13, v163
	v_lshlrev_b32_e32 v70, 16, v12
	v_and_b32_e32 v71, 0xffff0000, v12
	v_lshlrev_b32_e32 v66, 16, v13
	v_and_b32_e32 v67, 0xffff0000, v13
	v_pk_add_f32 v[68:69], v[68:69], v[70:71]
	v_pk_add_f32 v[64:65], v[64:65], v[66:67]
	s_waitcnt vmcnt(0)
	v_mov_b32_e32 v12, v164
	v_mov_b32_e32 v13, v165
	v_lshlrev_b32_e32 v72, 16, v12
	v_and_b32_e32 v73, 0xffff0000, v12
	v_lshlrev_b32_e32 v22, 16, v13
	v_and_b32_e32 v23, 0xffff0000, v13
	v_pk_add_f32 v[68:69], v[68:69], v[72:73]
	v_pk_add_f32 v[22:23], v[64:65], v[22:23]
	s_waitcnt vmcnt(0)
; DEVI unsigned pk_bf16(float lo, float hi) { unsigned r; asm volatile("v_cvt_pk_bf16_f32 %0, %1, %2" : "=v"(r) : "v"(lo), "v"(hi)); return r; }
; DEVI void ctx_combine_phase(const Params& p, int l, int gi, float coef, int ln, int lwhich) {
;     ...
;       for (int sl = 0; sl < 7; ++sl) {
;         const uint2 w = *((const uint2*)(PS + ((size_t)sl * TC + rc) * D) + lane + 64 * j);
;         sum[0] += __uint_as_float(w.x << 16); sum[1] += __uint_as_float(w.x & 0xffff0000u); sum[2] += __uint_as_float(w.y << 16); sum[3] += __uint_as_float(w.y & 0xffff0000u);
;       }
;       const f32x4 xo = x4[64 * j], gv = gate4[64 * j];
; #pragma unroll
;       for (int q = 0; q < 4; ++q) v[j][q] = xo[q] + coef * gv[q] * sum[q];
;       x4[64 * j] = v[j];
;       ss += (v[j][0] * v[j][0] + v[j][1] * v[j][1]) + (v[j][2] * v[j][2] + v[j][3] * v[j][3]);
;     }
;     if (ln >= 0) {
;       const f32x4* g4 = (const f32x4*)(p.in[6] + (size_t)(ln * 3 + lwhich) * D) + lane;
;       const f32x4* sh4 = (const f32x4*)(MOD + (size_t)((ln * 9 + 8) * 9 + lwhich * 3) * D) + lane;
;       const f32x4* sc4 = sh4 + D / 4;
;       const float rinv = rsqrtf(wave_sum(ss, lane) * (1.f / D) + 1e-6f);
;       uint2* o8 = (uint2*)(H + (size_t)(TL + rc) * D) + lane;
; #pragma unroll
;       for (int j = 0; j < 4; ++j) {
;         const f32x4 g = g4[64 * j], sh = sh4[64 * j], sc = sc4[64 * j];
;         f32x4 y;
; #pragma unroll
;         for (int q = 0; q < 4; ++q) y[q] = v[j][q] * rinv * g[q] * (1.f + sc[q]) + sh[q];
;         uint2 o; o.x = pk_bf16(y[0], y[1]); o.y = pk_bf16(y[2], y[3]); o8[64 * j] = o;
;       }
;     }
;   }
	v_mov_b32_e32 v12, v166
	v_mov_b32_e32 v13, v167
	v_lshlrev_b32_e32 v74, 16, v12
	v_and_b32_e32 v75, 0xffff0000, v12
	v_lshlrev_b32_e32 v52, 16, v13
	v_and_b32_e32 v53, 0xffff0000, v13
	v_pk_add_f32 v[68:69], v[68:69], v[74:75]
	v_pk_add_f32 v[22:23], v[22:23], v[52:53]
	v_lshl_add_u64 v[52:53], v[30:31], 0, v[16:17]
	s_waitcnt vmcnt(0)
	v_mov_b32_e32 v12, v168
	v_mov_b32_e32 v13, v169
	v_lshlrev_b32_e32 v76, 16, v12
	v_and_b32_e32 v77, 0xffff0000, v12
	v_lshlrev_b32_e32 v54, 16, v13
	v_and_b32_e32 v55, 0xffff0000, v13
	v_pk_add_f32 v[68:69], v[68:69], v[76:77]
	v_pk_add_f32 v[22:23], v[22:23], v[54:55]
	s_waitcnt vmcnt(0)
	v_mov_b32_e32 v12, v170
	v_mov_b32_e32 v13, v171
	v_lshlrev_b32_e32 v80, 16, v12
	v_and_b32_e32 v81, 0xffff0000, v12
	v_lshlrev_b32_e32 v56, 16, v13
	v_and_b32_e32 v57, 0xffff0000, v13
	v_pk_add_f32 v[68:69], v[68:69], v[80:81]
	v_pk_add_f32 v[22:23], v[22:23], v[56:57]
	v_lshl_add_u64 v[50:51], v[50:51], 0, s[10:11]
	s_waitcnt vmcnt(0)
	v_mov_b32_e32 v12, v172
	v_mov_b32_e32 v13, v173
	v_lshlrev_b32_e32 v82, 16, v12
	v_and_b32_e32 v83, 0xffff0000, v12
	v_lshlrev_b32_e32 v78, 16, v13
	v_and_b32_e32 v79, 0xffff0000, v13
	v_pk_add_f32 v[68:69], v[68:69], v[82:83]
	v_pk_add_f32 v[22:23], v[22:23], v[78:79]
	s_waitcnt vmcnt(0)
	v_mov_b32_e32 v84, v180
	v_mov_b32_e32 v85, v181
	v_mov_b32_e32 v86, v182
	v_mov_b32_e32 v87, v183
	v_mov_b32_e32 v12, v176
	v_mov_b32_e32 v13, v177
	v_mov_b32_e32 v14, v178
	v_mov_b32_e32 v15, v179
	v_pk_fma_f32 v[12:13], v[68:69], v[84:85], v[12:13]
	v_pk_fma_f32 v[14:15], v[22:23], v[86:87], v[14:15]
	global_store_dwordx4 v[18:19], v[12:15], off offset:3072
	v_pk_mul_f32 v[18:19], v[12:13], v[12:13]
	v_pk_mul_f32 v[22:23], v[14:15], v[14:15]
	v_mov_b32_e32 v21, v18
	v_mov_b32_e32 v59, v19
	v_mov_b32_e32 v61, v22
	v_mov_b32_e32 v63, v23
	v_pk_add_f32 v[18:19], v[20:21], v[58:59]
	v_pk_add_f32 v[20:21], v[60:61], v[62:63]
	s_nop 0
	v_pk_add_f32 v[18:19], v[18:19], v[20:21]
	s_nop 0
	v_add_f32_e32 v18, v18, v19
	ds_bpermute_b32 v19, v88, v18
	s_waitcnt lgkmcnt(0)
	v_add_f32_e32 v18, v18, v19
	ds_bpermute_b32 v19, v89, v18
	s_waitcnt lgkmcnt(0)
	v_add_f32_e32 v18, v18, v19
	ds_bpermute_b32 v19, v90, v18
	s_waitcnt lgkmcnt(0)
	v_add_f32_e32 v18, v18, v19
	ds_bpermute_b32 v19, v91, v18
	s_waitcnt lgkmcnt(0)
	v_add_f32_e32 v18, v18, v19
	ds_bpermute_b32 v19, v92, v18
	s_waitcnt lgkmcnt(0)
	v_add_f32_e32 v18, v18, v19
	ds_bpermute_b32 v19, v93, v18
	s_waitcnt lgkmcnt(0)
	v_add_f32_e32 v18, v18, v19
	v_fmamk_f32 v18, v18, 0x3a800000, v230
	v_cmp_gt_f32_e32 vcc, s8, v18
	v_mul_f32_e32 v19, 0x4b800000, v18
	s_nop 0
	v_cndmask_b32_e32 v18, v18, v19, vcc
	v_rsq_f32_e32 v18, v18
	s_nop 0
	v_mul_f32_e32 v19, 0x45800000, v18
	v_cndmask_b32_e32 v25, v18, v19, vcc
	global_load_dwordx4 v[20:23], v[48:49], off
	global_load_dwordx4 v[16:19], v[32:33], off
	global_load_dwordx4 v[54:57], v[34:35], off
	v_mul_f32_e32 v8, v8, v25
	v_mul_f32_e32 v9, v9, v25
	v_mul_f32_e32 v10, v10, v25
	v_mul_f32_e32 v11, v11, v25
	v_mul_f32_e32 v0, v0, v25
	v_mul_f32_e32 v1, v1, v25
	v_mul_f32_e32 v2, v2, v25
	v_mul_f32_e32 v3, v3, v25
	v_mul_f32_e32 v4, v4, v25
	v_mul_f32_e32 v12, v12, v25
	v_cmp_lt_i32_e32 vcc, s9, v24
	s_or_b64 s[6:7], vcc, s[6:7]
	s_waitcnt vmcnt(2)
	v_mul_f32_e32 v8, v20, v8
	v_mul_f32_e32 v9, v21, v9
	s_waitcnt vmcnt(0)
	v_add_f32_e32 v20, 1.0, v54
	v_fma_f32 v8, v20, v8, v16
	v_add_f32_e32 v16, 1.0, v55
	v_fma_f32 v9, v16, v9, v17
	v_mul_f32_e32 v10, v22, v10
	v_add_f32_e32 v16, 1.0, v56
	v_fma_f32 v10, v16, v10, v18
	v_mul_f32_e32 v11, v23, v11
	v_add_f32_e32 v16, 1.0, v57
	v_fmac_f32_e32 v19, v16, v11
	v_cvt_pk_bf16_f32 v8, v8, v9
	v_cvt_pk_bf16_f32 v9, v10, v19
	global_store_dwordx2 v[52:53], v[8:9], off
	global_load_dwordx4 v[8:11], v[48:49], off offset:1024
	s_nop 0
	global_load_dwordx4 v[16:19], v[36:37], off
	global_load_dwordx4 v[20:23], v[38:39], off
	s_waitcnt vmcnt(2)
	v_mul_f32_e32 v0, v8, v0
	v_mul_f32_e32 v1, v9, v1
	s_waitcnt vmcnt(0)
	v_add_f32_e32 v8, 1.0, v20
	v_fma_f32 v0, v8, v0, v16
	v_add_f32_e32 v8, 1.0, v21
	v_fma_f32 v1, v8, v1, v17
	v_mul_f32_e32 v2, v10, v2
	v_add_f32_e32 v8, 1.0, v22
	v_fma_f32 v2, v8, v2, v18
	v_mul_f32_e32 v3, v11, v3
	v_add_f32_e32 v8, 1.0, v23
	v_fmac_f32_e32 v19, v8, v3
	v_cvt_pk_bf16_f32 v0, v0, v1
	v_cvt_pk_bf16_f32 v1, v2, v19
	global_store_dwordx2 v[52:53], v[0:1], off offset:512
	global_load_dwordx4 v[0:3], v[48:49], off offset:2048
	s_nop 0
	global_load_dwordx4 v[8:11], v[40:41], off
	global_load_dwordx4 v[16:19], v[42:43], off
	s_waitcnt vmcnt(2)
	v_mul_f32_e32 v0, v4, v0
	s_waitcnt vmcnt(0)
	v_add_f32_e32 v4, 1.0, v16
	v_fma_f32 v0, v0, v4, v8
	v_mul_f32_e32 v4, v5, v25
	v_mul_f32_e32 v1, v4, v1
	v_add_f32_e32 v4, 1.0, v17
	v_fma_f32 v1, v1, v4, v9
	v_mul_f32_e32 v4, v6, v25
	v_mul_f32_e32 v2, v4, v2
	v_add_f32_e32 v4, 1.0, v18
	v_fma_f32 v2, v2, v4, v10
	v_mul_f32_e32 v4, v7, v25
	v_mul_f32_e32 v3, v4, v3
	v_add_f32_e32 v4, 1.0, v19
	v_fmac_f32_e32 v11, v3, v4
	v_cvt_pk_bf16_f32 v0, v0, v1
	v_cvt_pk_bf16_f32 v1, v2, v11
	global_store_dwordx2 v[52:53], v[0:1], off offset:1024
	global_load_dwordx4 v[0:3], v[48:49], off offset:3072
	s_nop 0
	global_load_dwordx4 v[4:7], v[44:45], off
	global_load_dwordx4 v[8:11], v[46:47], off
	s_waitcnt vmcnt(2)
	v_mul_f32_e32 v0, v12, v0
	s_waitcnt vmcnt(0)
	v_add_f32_e32 v8, 1.0, v8
	v_fma_f32 v0, v0, v8, v4
	v_mul_f32_e32 v4, v13, v25
	v_mul_f32_e32 v1, v4, v1
	v_add_f32_e32 v4, 1.0, v9
	v_fma_f32 v1, v1, v4, v5
	v_mul_f32_e32 v4, v14, v25
	v_mul_f32_e32 v2, v4, v2
	v_add_f32_e32 v4, 1.0, v10
	v_fma_f32 v2, v2, v4, v6
	v_mul_f32_e32 v4, v15, v25
	v_mul_f32_e32 v3, v4, v3
	v_add_f32_e32 v4, 1.0, v11
	v_fmac_f32_e32 v7, v3, v4
	v_cvt_pk_bf16_f32 v0, v0, v1
	v_cvt_pk_bf16_f32 v1, v2, v7
	global_store_dwordx2 v[52:53], v[0:1], off offset:1536
	s_andn2_b64 exec, exec, s[6:7]
	s_cbranch_execnz .LBB0_1929

; DEVI void ctx_combine_phase(const Params& p, int l, int gi, float coef, int ln, int lwhich) {
;     ...
;   for (int rc = gw; rc < TC; rc += NW) {
;     f32x4* x4 = (f32x4*)(X + (size_t)(TL + rc) * D) + lane;
;     f32x4 v[4]; float ss = 0.f;
; #pragma unroll
;     for (int j = 0; j < 4; ++j) {
;       f32x4 sum = {0.f, 0.f, 0.f, 0.f};
; #pragma unroll
;       for (int sl = 0; sl < 7; ++sl) {
;         const uint2 w = *((const uint2*)(PS + ((size_t)sl * TC + rc) * D) + lane + 64 * j);
;         sum[0] += __uint_as_float(w.x << 16); sum[1] += __uint_as_float(w.x & 0xffff0000u); sum[2] += __uint_as_float(w.y << 16); sum[3] += __uint_as_float(w.y & 0xffff0000u);
;       }
;       const f32x4 xo = x4[64 * j], gv = gate4[64 * j];
; #pragma unroll
;       for (int q = 0; q < 4; ++q) v[j][q] = xo[q] + coef * gv[q] * sum[q];
;       x4[64 * j] = v[j];
;       ss += (v[j][0] * v[j][0] + v[j][1] * v[j][1]) + (v[j][2] * v[j][2] + v[j][3] * v[j][3]);
.LBB0_2426:
	v_add_co_u32_e32 v12, vcc, 0xfe800000, v50
	v_add_u32_e32 v16, 0x8000, v24
	s_nop 0
	v_addc_co_u32_e32 v13, vcc, -1, v51, vcc
	v_add_co_u32_e32 v14, vcc, 0xfec00000, v50
	v_ashrrev_i32_e32 v17, 31, v16
	s_nop 0
	v_addc_co_u32_e32 v15, vcc, -1, v51, vcc
	v_add_co_u32_e32 v22, vcc, 0xff000000, v50
	v_lshlrev_b64 v[0:1], 12, v[16:17]
	s_nop 0
	v_addc_co_u32_e32 v23, vcc, -1, v51, vcc
	v_add_co_u32_e32 v52, vcc, 0xff400000, v50
	v_lshl_add_u64 v[18:19], v[28:29], 0, v[0:1]
	s_nop 0
	v_addc_co_u32_e32 v53, vcc, -1, v51, vcc
	v_add_co_u32_e32 v54, vcc, 0xff800000, v50
	global_load_dwordx2 v[10:11], v[52:53], off offset:-1540
	s_nop 0
	v_addc_co_u32_e32 v55, vcc, -1, v51, vcc
	global_load_dwordx2 v[56:57], v[54:55], off offset:-1540
	global_load_dwordx2 v[0:1], v[12:13], off offset:-1540
	global_load_dwordx2 v[2:3], v[14:15], off offset:-1540
	global_load_dwordx2 v[6:7], v[22:23], off offset:-1540
	v_add_co_u32_e32 v98, vcc, 0xffc00000, v50
	s_nop 1
	v_addc_co_u32_e32 v99, vcc, -1, v51, vcc
	global_load_dwordx2 v[100:101], v[98:99], off offset:-1540
	global_load_dwordx2 v[102:103], v[50:51], off offset:-1540
	global_load_dwordx4 v[104:107], v[18:19], off
	global_load_dwordx4 v[108:111], v[26:27], off
	global_load_dwordx2 v[112:113], v[12:13], off offset:-1028
	global_load_dwordx2 v[114:115], v[14:15], off offset:-1028
	global_load_dwordx2 v[116:117], v[22:23], off offset:-1028
	global_load_dwordx2 v[118:119], v[52:53], off offset:-1028
	global_load_dwordx2 v[120:121], v[54:55], off offset:-1028
	global_load_dwordx2 v[122:123], v[98:99], off offset:-1028
	global_load_dwordx2 v[124:125], v[50:51], off offset:-1028
	global_load_dwordx4 v[126:129], v[18:19], off offset:1024
	global_load_dwordx4 v[130:133], v[26:27], off offset:1024
	global_load_dwordx2 v[134:135], v[12:13], off offset:-516
	global_load_dwordx2 v[136:137], v[14:15], off offset:-516
	global_load_dwordx2 v[138:139], v[22:23], off offset:-516
	global_load_dwordx2 v[140:141], v[52:53], off offset:-516
	global_load_dwordx2 v[142:143], v[54:55], off offset:-516
	global_load_dwordx2 v[144:145], v[98:99], off offset:-516
	global_load_dwordx2 v[146:147], v[50:51], off offset:-516
	global_load_dwordx4 v[152:155], v[18:19], off offset:2048
	global_load_dwordx4 v[156:159], v[26:27], off offset:2048
	global_load_dwordx2 v[160:161], v[12:13], off offset:-4
	global_load_dwordx2 v[162:163], v[14:15], off offset:-4
	global_load_dwordx2 v[164:165], v[22:23], off offset:-4
	global_load_dwordx2 v[166:167], v[52:53], off offset:-4
	global_load_dwordx2 v[168:169], v[54:55], off offset:-4
	global_load_dwordx2 v[170:171], v[98:99], off offset:-4
	global_load_dwordx2 v[172:173], v[50:51], off offset:-4
	global_load_dwordx4 v[176:179], v[18:19], off offset:3072
	global_load_dwordx4 v[180:183], v[26:27], off offset:3072
	v_lshlrev_b64 v[16:17], 11, v[16:17]
	v_add_u32_e32 v24, s2, v24
	s_waitcnt vmcnt(4)
	v_lshlrev_b32_e32 v60, 16, v10
	v_and_b32_e32 v61, 0xffff0000, v10
	v_lshlrev_b32_e32 v10, 16, v11
	s_waitcnt vmcnt(3)
	v_lshlrev_b32_e32 v70, 16, v56
	v_and_b32_e32 v71, 0xffff0000, v56
	v_add_co_u32_e32 v56, vcc, 0xffc00000, v50
	v_lshlrev_b32_e32 v58, 16, v57
	v_and_b32_e32 v59, 0xffff0000, v57
	v_addc_co_u32_e32 v57, vcc, -1, v51, vcc
	v_and_b32_e32 v11, 0xffff0000, v11
	s_waitcnt vmcnt(0)
	v_mov_b32_e32 v62, v100
	v_mov_b32_e32 v63, v101
	v_lshlrev_b32_e32 v72, 16, v62
	v_and_b32_e32 v73, 0xffff0000, v62
	v_lshlrev_b32_e32 v74, 16, v63
	v_and_b32_e32 v75, 0xffff0000, v63
	v_lshlrev_b32_e32 v4, 16, v0
	v_and_b32_e32 v5, 0xffff0000, v0
	v_lshlrev_b32_e32 v0, 16, v1
	v_and_b32_e32 v1, 0xffff0000, v1
	v_lshlrev_b32_e32 v8, 16, v2
	v_and_b32_e32 v9, 0xffff0000, v2
	v_lshlrev_b32_e32 v2, 16, v3
	v_and_b32_e32 v3, 0xffff0000, v3
	v_pk_add_f32 v[4:5], v[4:5], 0 op_sel_hi:[1,0]
	v_pk_add_f32 v[0:1], v[0:1], 0 op_sel_hi:[1,0]
	v_lshlrev_b32_e32 v20, 16, v6
	v_and_b32_e32 v21, 0xffff0000, v6
	v_lshlrev_b32_e32 v6, 16, v7
	v_and_b32_e32 v7, 0xffff0000, v7
	v_pk_add_f32 v[4:5], v[4:5], v[8:9]
	v_pk_add_f32 v[0:1], v[0:1], v[2:3]
	v_pk_add_f32 v[4:5], v[4:5], v[20:21]
	v_pk_add_f32 v[0:1], v[0:1], v[6:7]
	v_pk_add_f32 v[4:5], v[4:5], v[60:61]
	v_pk_add_f32 v[0:1], v[0:1], v[10:11]
	v_pk_add_f32 v[4:5], v[4:5], v[70:71]
	v_pk_add_f32 v[0:1], v[0:1], v[58:59]
	v_pk_add_f32 v[4:5], v[4:5], v[72:73]
	v_pk_add_f32 v[0:1], v[0:1], v[74:75]
	s_waitcnt vmcnt(0)
	v_mov_b32_e32 v62, v102
	v_mov_b32_e32 v63, v103
	v_lshlrev_b32_e32 v76, 16, v62
	v_and_b32_e32 v77, 0xffff0000, v62
	v_lshlrev_b32_e32 v78, 16, v63
	v_and_b32_e32 v79, 0xffff0000, v63
	v_pk_add_f32 v[4:5], v[4:5], v[76:77]
	v_pk_add_f32 v[0:1], v[0:1], v[78:79]
	s_waitcnt vmcnt(0)
	v_mov_b32_e32 v66, v108
	v_mov_b32_e32 v67, v109
	v_mov_b32_e32 v68, v110
	v_mov_b32_e32 v69, v111
	v_mov_b32_e32 v62, v104
	v_mov_b32_e32 v63, v105
	v_mov_b32_e32 v64, v106
	v_mov_b32_e32 v65, v107
	v_pk_mul_f32 v[8:9], v[66:67], 0.5 op_sel_hi:[1,0]
	v_pk_mul_f32 v[2:3], v[68:69], 0.5 op_sel_hi:[1,0]
	v_pk_fma_f32 v[8:9], v[4:5], v[8:9], v[62:63]
	v_pk_fma_f32 v[10:11], v[0:1], v[2:3], v[64:65]
	v_mov_b32_e32 v2, v9
	v_mov_b32_e32 v3, v11
	v_mov_b32_e32 v0, v8
	v_mov_b32_e32 v1, v10
	v_pk_mul_f32 v[2:3], v[2:3], v[2:3]
	global_store_dwordx4 v[18:19], v[8:11], off
	v_pk_fma_f32 v[0:1], v[0:1], v[0:1], v[2:3]
	s_nop 0
	v_pk_add_f32 v[20:21], v[0:1], v[0:1] op_sel:[0,1] op_sel_hi:[1,0]
	s_waitcnt vmcnt(0)
	v_mov_b32_e32 v0, v112
	v_mov_b32_e32 v1, v113
	v_lshlrev_b32_e32 v58, 16, v0
	v_and_b32_e32 v59, 0xffff0000, v0
	v_lshlrev_b32_e32 v4, 16, v1
	v_and_b32_e32 v5, 0xffff0000, v1
	v_pk_add_f32 v[58:59], v[58:59], 0 op_sel_hi:[1,0]
	v_pk_add_f32 v[4:5], v[4:5], 0 op_sel_hi:[1,0]
	s_waitcnt vmcnt(0)
; DEVI void ctx_combine_phase(const Params& p, int l, int gi, float coef, int ln, int lwhich) {
;     ...
;     for (int j = 0; j < 4; ++j) {
;       f32x4 sum = {0.f, 0.f, 0.f, 0.f};
; #pragma unroll
;       for (int sl = 0; sl < 7; ++sl) {
;         const uint2 w = *((const uint2*)(PS + ((size_t)sl * TC + rc) * D) + lane + 64 * j);
;         sum[0] += __uint_as_float(w.x << 16); sum[1] += __uint_as_float(w.x & 0xffff0000u); sum[2] += __uint_as_float(w.y << 16); sum[3] += __uint_as_float(w.y & 0xffff0000u);
;       }
;       const f32x4 xo = x4[64 * j], gv = gate4[64 * j];
; #pragma unroll
;       for (int q = 0; q < 4; ++q) v[j][q] = xo[q] + coef * gv[q] * sum[q];
;       x4[64 * j] = v[j];
;       ss += (v[j][0] * v[j][0] + v[j][1] * v[j][1]) + (v[j][2] * v[j][2] + v[j][3] * v[j][3]);
	v_mov_b32_e32 v0, v114
	v_mov_b32_e32 v1, v115
	v_lshlrev_b32_e32 v62, 16, v0
	v_and_b32_e32 v63, 0xffff0000, v0
	v_lshlrev_b32_e32 v6, 16, v1
	v_and_b32_e32 v7, 0xffff0000, v1
	v_pk_add_f32 v[58:59], v[58:59], v[62:63]
	v_pk_add_f32 v[4:5], v[4:5], v[6:7]
	s_waitcnt vmcnt(0)
	v_mov_b32_e32 v0, v116
	v_mov_b32_e32 v1, v117
	v_lshlrev_b32_e32 v66, 16, v0
	v_and_b32_e32 v67, 0xffff0000, v0
	v_lshlrev_b32_e32 v60, 16, v1
	v_and_b32_e32 v61, 0xffff0000, v1
	v_pk_add_f32 v[58:59], v[58:59], v[66:67]
	v_pk_add_f32 v[4:5], v[4:5], v[60:61]
	s_waitcnt vmcnt(0)
	v_mov_b32_e32 v0, v118
	v_mov_b32_e32 v1, v119
	v_lshlrev_b32_e32 v70, 16, v0
	v_and_b32_e32 v71, 0xffff0000, v0
	v_lshlrev_b32_e32 v64, 16, v1
	v_and_b32_e32 v65, 0xffff0000, v1
	v_pk_add_f32 v[58:59], v[58:59], v[70:71]
	v_pk_add_f32 v[4:5], v[4:5], v[64:65]
	s_waitcnt vmcnt(0)
	v_mov_b32_e32 v0, v120
	v_mov_b32_e32 v1, v121
	v_lshlrev_b32_e32 v74, 16, v0
	v_and_b32_e32 v75, 0xffff0000, v0
	v_lshlrev_b32_e32 v68, 16, v1
	v_and_b32_e32 v69, 0xffff0000, v1
	v_pk_add_f32 v[58:59], v[58:59], v[74:75]
	v_pk_add_f32 v[4:5], v[4:5], v[68:69]
	s_waitcnt vmcnt(0)
	v_mov_b32_e32 v0, v122
	v_mov_b32_e32 v1, v123
	v_lshlrev_b32_e32 v78, 16, v0
	v_and_b32_e32 v79, 0xffff0000, v0
	v_lshlrev_b32_e32 v72, 16, v1
	v_and_b32_e32 v73, 0xffff0000, v1
	v_pk_add_f32 v[58:59], v[58:59], v[78:79]
	v_pk_add_f32 v[4:5], v[4:5], v[72:73]
	s_waitcnt vmcnt(0)
	v_mov_b32_e32 v0, v124
	v_mov_b32_e32 v1, v125
	v_lshlrev_b32_e32 v80, 16, v0
	v_and_b32_e32 v81, 0xffff0000, v0
	v_lshlrev_b32_e32 v76, 16, v1
	v_and_b32_e32 v77, 0xffff0000, v1
	v_pk_add_f32 v[58:59], v[58:59], v[80:81]
	v_pk_add_f32 v[4:5], v[4:5], v[76:77]
	s_waitcnt vmcnt(0)
	v_mov_b32_e32 v82, v130
	v_mov_b32_e32 v83, v131
	v_mov_b32_e32 v84, v132
	v_mov_b32_e32 v85, v133
	v_mov_b32_e32 v0, v126
	v_mov_b32_e32 v1, v127
	v_mov_b32_e32 v2, v128
	v_mov_b32_e32 v3, v129
	v_pk_mul_f32 v[62:63], v[82:83], 0.5 op_sel_hi:[1,0]
	v_pk_mul_f32 v[6:7], v[84:85], 0.5 op_sel_hi:[1,0]
	v_pk_fma_f32 v[0:1], v[58:59], v[62:63], v[0:1]
	v_pk_fma_f32 v[2:3], v[4:5], v[6:7], v[2:3]
	v_mov_b32_e32 v6, v1
	v_mov_b32_e32 v7, v3
	v_mov_b32_e32 v4, v0
	v_mov_b32_e32 v5, v2
	v_pk_mul_f32 v[6:7], v[6:7], v[6:7]
	global_store_dwordx4 v[18:19], v[0:3], off offset:1024
	v_pk_fma_f32 v[4:5], v[4:5], v[4:5], v[6:7]
	s_nop 0
	v_pk_add_f32 v[58:59], v[4:5], v[4:5] op_sel:[0,1] op_sel_hi:[1,0]
	s_waitcnt vmcnt(0)
	v_mov_b32_e32 v4, v134
	v_mov_b32_e32 v5, v135
	v_lshlrev_b32_e32 v64, 16, v4
	v_and_b32_e32 v65, 0xffff0000, v4
	v_lshlrev_b32_e32 v60, 16, v5
	v_and_b32_e32 v61, 0xffff0000, v5
	v_pk_add_f32 v[64:65], v[64:65], 0 op_sel_hi:[1,0]
	v_pk_add_f32 v[60:61], v[60:61], 0 op_sel_hi:[1,0]
	s_waitcnt vmcnt(0)
	v_mov_b32_e32 v4, v136
	v_mov_b32_e32 v5, v137
	v_lshlrev_b32_e32 v68, 16, v4
	v_and_b32_e32 v69, 0xffff0000, v4
	v_lshlrev_b32_e32 v62, 16, v5
	v_and_b32_e32 v63, 0xffff0000, v5
	v_pk_add_f32 v[64:65], v[64:65], v[68:69]
	v_pk_add_f32 v[60:61], v[60:61], v[62:63]
	s_waitcnt vmcnt(0)
	v_mov_b32_e32 v4, v138
	v_mov_b32_e32 v5, v139
	v_lshlrev_b32_e32 v72, 16, v4
	v_and_b32_e32 v73, 0xffff0000, v4
	v_lshlrev_b32_e32 v66, 16, v5
	v_and_b32_e32 v67, 0xffff0000, v5
	v_pk_add_f32 v[64:65], v[64:65], v[72:73]
	v_pk_add_f32 v[60:61], v[60:61], v[66:67]
	s_waitcnt vmcnt(0)
	v_mov_b32_e32 v4, v140
	v_mov_b32_e32 v5, v141
	v_lshlrev_b32_e32 v76, 16, v4
	v_and_b32_e32 v77, 0xffff0000, v4
	v_lshlrev_b32_e32 v70, 16, v5
	v_and_b32_e32 v71, 0xffff0000, v5
	v_pk_add_f32 v[64:65], v[64:65], v[76:77]
	v_pk_add_f32 v[60:61], v[60:61], v[70:71]
	s_waitcnt vmcnt(0)
	v_mov_b32_e32 v4, v142
	v_mov_b32_e32 v5, v143
	v_lshlrev_b32_e32 v80, 16, v4
	v_and_b32_e32 v81, 0xffff0000, v4
	v_lshlrev_b32_e32 v74, 16, v5
	v_and_b32_e32 v75, 0xffff0000, v5
	v_pk_add_f32 v[64:65], v[64:65], v[80:81]
	v_pk_add_f32 v[60:61], v[60:61], v[74:75]
	s_waitcnt vmcnt(0)
	v_mov_b32_e32 v4, v144
	v_mov_b32_e32 v5, v145
	v_lshlrev_b32_e32 v84, 16, v4
	v_and_b32_e32 v85, 0xffff0000, v4
	v_lshlrev_b32_e32 v78, 16, v5
	v_and_b32_e32 v79, 0xffff0000, v5
	v_pk_add_f32 v[64:65], v[64:65], v[84:85]
	v_pk_add_f32 v[60:61], v[60:61], v[78:79]
	s_waitcnt vmcnt(0)
	v_mov_b32_e32 v4, v146
	v_mov_b32_e32 v5, v147
	v_lshlrev_b32_e32 v86, 16, v4
	v_and_b32_e32 v87, 0xffff0000, v4
	v_lshlrev_b32_e32 v82, 16, v5
	v_and_b32_e32 v83, 0xffff0000, v5
	v_pk_add_f32 v[64:65], v[64:65], v[86:87]
	v_pk_add_f32 v[60:61], v[60:61], v[82:83]
	s_waitcnt vmcnt(0)
	v_mov_b32_e32 v94, v156
	v_mov_b32_e32 v95, v157
	v_mov_b32_e32 v96, v158
	v_mov_b32_e32 v97, v159
	v_mov_b32_e32 v4, v152
	v_mov_b32_e32 v5, v153
	v_mov_b32_e32 v6, v154
	v_mov_b32_e32 v7, v155
	v_pk_mul_f32 v[68:69], v[94:95], 0.5 op_sel_hi:[1,0]
	v_pk_mul_f32 v[62:63], v[96:97], 0.5 op_sel_hi:[1,0]
	v_pk_fma_f32 v[4:5], v[64:65], v[68:69], v[4:5]
	v_pk_fma_f32 v[6:7], v[60:61], v[62:63], v[6:7]
	global_store_dwordx4 v[18:19], v[4:7], off offset:2048
	v_mul_f32_e32 v60, v5, v5
	v_mul_f32_e32 v62, v7, v7
	v_pk_fma_f32 v[60:61], v[4:5], v[4:5], v[60:61] op_sel_hi:[1,1,0]
	v_pk_fma_f32 v[62:63], v[6:7], v[6:7], v[62:63] op_sel_hi:[1,1,0]
	s_waitcnt vmcnt(0)
	v_mov_b32_e32 v12, v160
	v_mov_b32_e32 v13, v161
	v_lshlrev_b32_e32 v68, 16, v12
	v_and_b32_e32 v69, 0xffff0000, v12
	v_lshlrev_b32_e32 v64, 16, v13
	v_and_b32_e32 v65, 0xffff0000, v13
	v_pk_add_f32 v[68:69], v[68:69], 0 op_sel_hi:[1,0]
	v_pk_add_f32 v[64:65], v[64:65], 0 op_sel_hi:[1,0]
	s_waitcnt vmcnt(0)
	v_mov_b32_e32 v12, v162
	v_mov_b32_e32 v13, v163
	v_lshlrev_b32_e32 v70, 16, v12
	v_and_b32_e32 v71, 0xffff0000, v12
	v_lshlrev_b32_e32 v66, 16, v13
	v_and_b32_e32 v67, 0xffff0000, v13
	v_pk_add_f32 v[68:69], v[68:69], v[70:71]
	v_pk_add_f32 v[64:65], v[64:65], v[66:67]
	s_waitcnt vmcnt(0)
; DEVI unsigned pk_bf16(float lo, float hi) { unsigned r; asm volatile("v_cvt_pk_bf16_f32 %0, %1, %2" : "=v"(r) : "v"(lo), "v"(hi)); return r; }
; DEVI void ctx_combine_phase(const Params& p, int l, int gi, float coef, int ln, int lwhich) {
;     ...
;       for (int sl = 0; sl < 7; ++sl) {
;         const uint2 w = *((const uint2*)(PS + ((size_t)sl * TC + rc) * D) + lane + 64 * j);
;         sum[0] += __uint_as_float(w.x << 16); sum[1] += __uint_as_float(w.x & 0xffff0000u); sum[2] += __uint_as_float(w.y << 16); sum[3] += __uint_as_float(w.y & 0xffff0000u);
;       }
;       const f32x4 xo = x4[64 * j], gv = gate4[64 * j];
; #pragma unroll
;       for (int q = 0; q < 4; ++q) v[j][q] = xo[q] + coef * gv[q] * sum[q];
;       x4[64 * j] = v[j];
;       ss += (v[j][0] * v[j][0] + v[j][1] * v[j][1]) + (v[j][2] * v[j][2] + v[j][3] * v[j][3]);
;     }
;     if (ln >= 0) {
;       const f32x4* g4 = (const f32x4*)(p.in[6] + (size_t)(ln * 3 + lwhich) * D) + lane;
;       const f32x4* sh4 = (const f32x4*)(MOD + (size_t)((ln * 9 + 8) * 9 + lwhich * 3) * D) + lane;
;       const f32x4* sc4 = sh4 + D / 4;
;       const float rinv = rsqrtf(wave_sum(ss, lane) * (1.f / D) + 1e-6f);
;       uint2* o8 = (uint2*)(H + (size_t)(TL + rc) * D) + lane;
; #pragma unroll
;       for (int j = 0; j < 4; ++j) {
;         const f32x4 g = g4[64 * j], sh = sh4[64 * j], sc = sc4[64 * j];
;         f32x4 y;
; #pragma unroll
;         for (int q = 0; q < 4; ++q) y[q] = v[j][q] * rinv * g[q] * (1.f + sc[q]) + sh[q];
;         uint2 o; o.x = pk_bf16(y[0], y[1]); o.y = pk_bf16(y[2], y[3]); o8[64 * j] = o;
;       }
;     }
;   }
	v_mov_b32_e32 v12, v164
	v_mov_b32_e32 v13, v165
	v_lshlrev_b32_e32 v72, 16, v12
	v_and_b32_e32 v73, 0xffff0000, v12
	v_lshlrev_b32_e32 v22, 16, v13
	v_and_b32_e32 v23, 0xffff0000, v13
	v_pk_add_f32 v[68:69], v[68:69], v[72:73]
	v_pk_add_f32 v[22:23], v[64:65], v[22:23]
	s_waitcnt vmcnt(0)
	v_mov_b32_e32 v12, v166
	v_mov_b32_e32 v13, v167
	v_lshlrev_b32_e32 v74, 16, v12
	v_and_b32_e32 v75, 0xffff0000, v12
	v_lshlrev_b32_e32 v52, 16, v13
	v_and_b32_e32 v53, 0xffff0000, v13
	v_pk_add_f32 v[68:69], v[68:69], v[74:75]
	v_pk_add_f32 v[22:23], v[22:23], v[52:53]
	s_waitcnt vmcnt(0)
	v_mov_b32_e32 v12, v168
	v_mov_b32_e32 v13, v169
	v_lshlrev_b32_e32 v76, 16, v12
	v_and_b32_e32 v77, 0xffff0000, v12
	v_lshlrev_b32_e32 v54, 16, v13
	v_and_b32_e32 v55, 0xffff0000, v13
	v_pk_add_f32 v[68:69], v[68:69], v[76:77]
	v_pk_add_f32 v[22:23], v[22:23], v[54:55]
	s_waitcnt vmcnt(0)
	v_mov_b32_e32 v12, v170
	v_mov_b32_e32 v13, v171
	v_lshlrev_b32_e32 v80, 16, v12
	v_and_b32_e32 v81, 0xffff0000, v12
	v_lshlrev_b32_e32 v56, 16, v13
	v_and_b32_e32 v57, 0xffff0000, v13
	v_pk_add_f32 v[68:69], v[68:69], v[80:81]
	v_pk_add_f32 v[22:23], v[22:23], v[56:57]
	v_lshl_add_u64 v[50:51], v[50:51], 0, s[10:11]
	s_waitcnt vmcnt(0)
	v_mov_b32_e32 v12, v172
	v_mov_b32_e32 v13, v173
	v_lshlrev_b32_e32 v82, 16, v12
	v_and_b32_e32 v83, 0xffff0000, v12
	v_lshlrev_b32_e32 v78, 16, v13
	v_and_b32_e32 v79, 0xffff0000, v13
	v_pk_add_f32 v[68:69], v[68:69], v[82:83]
	v_pk_add_f32 v[22:23], v[22:23], v[78:79]
	s_waitcnt vmcnt(0)
	v_mov_b32_e32 v84, v180
	v_mov_b32_e32 v85, v181
	v_mov_b32_e32 v86, v182
	v_mov_b32_e32 v87, v183
	v_mov_b32_e32 v12, v176
	v_mov_b32_e32 v13, v177
	v_mov_b32_e32 v14, v178
	v_mov_b32_e32 v15, v179
	v_pk_mul_f32 v[70:71], v[84:85], 0.5 op_sel_hi:[1,0]
	v_pk_mul_f32 v[52:53], v[86:87], 0.5 op_sel_hi:[1,0]
	v_pk_fma_f32 v[12:13], v[68:69], v[70:71], v[12:13]
	v_pk_fma_f32 v[14:15], v[22:23], v[52:53], v[14:15]
	global_store_dwordx4 v[18:19], v[12:15], off offset:3072
	v_pk_mul_f32 v[18:19], v[12:13], v[12:13]
	v_pk_mul_f32 v[22:23], v[14:15], v[14:15]
	v_mov_b32_e32 v21, v18
	v_mov_b32_e32 v59, v19
	v_mov_b32_e32 v61, v22
	v_mov_b32_e32 v63, v23
	v_pk_add_f32 v[18:19], v[20:21], v[58:59]
	v_pk_add_f32 v[20:21], v[60:61], v[62:63]
	v_lshl_add_u64 v[52:53], v[30:31], 0, v[16:17]
	v_pk_add_f32 v[18:19], v[18:19], v[20:21]
	s_nop 0
	v_add_f32_e32 v18, v18, v19
	ds_bpermute_b32 v19, v88, v18
	s_waitcnt lgkmcnt(0)
	v_add_f32_e32 v18, v18, v19
	ds_bpermute_b32 v19, v89, v18
	s_waitcnt lgkmcnt(0)
	v_add_f32_e32 v18, v18, v19
	ds_bpermute_b32 v19, v90, v18
	s_waitcnt lgkmcnt(0)
	v_add_f32_e32 v18, v18, v19
	ds_bpermute_b32 v19, v91, v18
	s_waitcnt lgkmcnt(0)
	v_add_f32_e32 v18, v18, v19
	ds_bpermute_b32 v19, v92, v18
	s_waitcnt lgkmcnt(0)
	v_add_f32_e32 v18, v18, v19
	ds_bpermute_b32 v19, v93, v18
	s_waitcnt lgkmcnt(0)
	v_add_f32_e32 v18, v18, v19
	v_fmamk_f32 v18, v18, 0x3a800000, v230
	v_cmp_gt_f32_e32 vcc, s8, v18
	v_mul_f32_e32 v19, 0x4b800000, v18
	s_nop 0
	v_cndmask_b32_e32 v18, v18, v19, vcc
	v_rsq_f32_e32 v18, v18
	s_nop 0
	v_mul_f32_e32 v19, 0x45800000, v18
	v_cndmask_b32_e32 v25, v18, v19, vcc
	global_load_dwordx4 v[20:23], v[48:49], off
	global_load_dwordx4 v[16:19], v[32:33], off
	global_load_dwordx4 v[54:57], v[34:35], off
	v_mul_f32_e32 v8, v8, v25
	v_mul_f32_e32 v9, v9, v25
	v_mul_f32_e32 v10, v10, v25
	v_mul_f32_e32 v11, v11, v25
	v_mul_f32_e32 v0, v0, v25
	v_mul_f32_e32 v1, v1, v25
	v_mul_f32_e32 v2, v2, v25
	v_mul_f32_e32 v3, v3, v25
	v_mul_f32_e32 v4, v4, v25
	v_mul_f32_e32 v12, v12, v25
	v_cmp_lt_i32_e32 vcc, s24, v24
	s_or_b64 s[6:7], vcc, s[6:7]
	s_waitcnt vmcnt(2)
	v_mul_f32_e32 v8, v20, v8
	v_mul_f32_e32 v9, v21, v9
	s_waitcnt vmcnt(0)
	v_add_f32_e32 v20, 1.0, v54
	v_fma_f32 v8, v20, v8, v16
	v_add_f32_e32 v16, 1.0, v55
	v_fma_f32 v9, v16, v9, v17
	v_mul_f32_e32 v10, v22, v10
	v_add_f32_e32 v16, 1.0, v56
	v_fma_f32 v10, v16, v10, v18
	v_mul_f32_e32 v11, v23, v11
	v_add_f32_e32 v16, 1.0, v57
	v_fmac_f32_e32 v19, v16, v11
	v_cvt_pk_bf16_f32 v8, v8, v9
	v_cvt_pk_bf16_f32 v9, v10, v19
	global_store_dwordx2 v[52:53], v[8:9], off
	global_load_dwordx4 v[8:11], v[48:49], off offset:1024
	s_nop 0
	global_load_dwordx4 v[16:19], v[36:37], off
	global_load_dwordx4 v[20:23], v[38:39], off
	s_waitcnt vmcnt(2)
	v_mul_f32_e32 v0, v8, v0
	v_mul_f32_e32 v1, v9, v1
	s_waitcnt vmcnt(0)
	v_add_f32_e32 v8, 1.0, v20
	v_fma_f32 v0, v8, v0, v16
	v_add_f32_e32 v8, 1.0, v21
	v_fma_f32 v1, v8, v1, v17
	v_mul_f32_e32 v2, v10, v2
	v_add_f32_e32 v8, 1.0, v22
	v_fma_f32 v2, v8, v2, v18
	v_mul_f32_e32 v3, v11, v3
	v_add_f32_e32 v8, 1.0, v23
	v_fmac_f32_e32 v19, v8, v3
	v_cvt_pk_bf16_f32 v0, v0, v1
	v_cvt_pk_bf16_f32 v1, v2, v19
	global_store_dwordx2 v[52:53], v[0:1], off offset:512
	global_load_dwordx4 v[0:3], v[48:49], off offset:2048
	s_nop 0
	global_load_dwordx4 v[8:11], v[40:41], off
	global_load_dwordx4 v[16:19], v[42:43], off
	s_waitcnt vmcnt(2)
	v_mul_f32_e32 v0, v4, v0
	s_waitcnt vmcnt(0)
	v_add_f32_e32 v4, 1.0, v16
	v_fma_f32 v0, v0, v4, v8
	v_mul_f32_e32 v4, v5, v25
	v_mul_f32_e32 v1, v4, v1
	v_add_f32_e32 v4, 1.0, v17
	v_fma_f32 v1, v1, v4, v9
	v_mul_f32_e32 v4, v6, v25
	v_mul_f32_e32 v2, v4, v2
	v_add_f32_e32 v4, 1.0, v18
	v_fma_f32 v2, v2, v4, v10
	v_mul_f32_e32 v4, v7, v25
	v_mul_f32_e32 v3, v4, v3
	v_add_f32_e32 v4, 1.0, v19
	v_fmac_f32_e32 v11, v3, v4
	v_cvt_pk_bf16_f32 v0, v0, v1
	v_cvt_pk_bf16_f32 v1, v2, v11
	global_store_dwordx2 v[52:53], v[0:1], off offset:1024
	global_load_dwordx4 v[0:3], v[48:49], off offset:3072
	s_nop 0
	global_load_dwordx4 v[4:7], v[44:45], off
	global_load_dwordx4 v[8:11], v[46:47], off
	s_waitcnt vmcnt(2)
	v_mul_f32_e32 v0, v12, v0
	s_waitcnt vmcnt(0)
	v_add_f32_e32 v8, 1.0, v8
	v_fma_f32 v0, v0, v8, v4
	v_mul_f32_e32 v4, v13, v25
	v_mul_f32_e32 v1, v4, v1
	v_add_f32_e32 v4, 1.0, v9
	v_fma_f32 v1, v1, v4, v5
	v_mul_f32_e32 v4, v14, v25
	v_mul_f32_e32 v2, v4, v2
	v_add_f32_e32 v4, 1.0, v10
	v_fma_f32 v2, v2, v4, v6
	v_mul_f32_e32 v4, v15, v25
	v_mul_f32_e32 v3, v4, v3
	v_add_f32_e32 v4, 1.0, v11
	v_fmac_f32_e32 v7, v3, v4
	v_cvt_pk_bf16_f32 v0, v0, v1
	v_cvt_pk_bf16_f32 v1, v2, v7
	global_store_dwordx2 v[52:53], v[0:1], off offset:1536
	s_andn2_b64 exec, exec, s[6:7]
	s_cbranch_execnz .LBB0_2426
